# gla_scan unit rewritten: GA/GK chunk shares loaded coalesced once per workgroup and exchanged through LDS (was 8x redundant strided loads), packed z/log-sigmoid, SGPR addressing, distance-2 prefetch
# speedup vs baseline: 1.0075x; 1.0075x over previous
;     ...
;     for (int u = vb; u < 256; u += nb) {
;         const int b = u >> 5, hh = (u >> 3) & 3, ksl = u & 7;
;         const int kc0 = hh * 128 + ksl * 16 + 2 * w;
;         float wa[2][16], bb[2];
; #pragma unroll
;         for (int e = 0; e < 2; ++e) { bb[e] = ba[kc0 + e];
; #pragma unroll
;             for (int jj = 0; jj < 16; ++jj) wa[e][jj] = w2[jj * 512 + kc0 + e]; }
;         f32x4 acc[2];
; #pragma unroll
;         for (int e = 0; e < 2; ++e) acc[e] = (f32x4){0.f, 0.f, 0.f, 0.f};
;         __syncthreads();
;         f32x4 a4n[4]; unsigned krawn; bf16x8 vfrn[2][2];
;         auto ldchunk = [&](int n) {
;             const int tok = b * 4096 + n * 64 + l;
; #pragma unroll
;             for (int q = 0; q < 4; ++q) a4n[q] = *(const f32x4*)(GA + (size_t)tok * 16 + 4 * q);
;             krawn = *(const unsigned*)(GK + (size_t)tok * 512 + kc0);
; #pragma unroll
;             for (int e = 0; e < 2; ++e)
; #pragma unroll
;                 for (int ks = 0; ks < 2; ++ks)
;                     vfrn[e][ks] = *(const bf16x8*)(GVT + ((size_t)(b * 1024 + hh * 256 + (2 * w + e) * 16 + (l & 15))) * 4096 + n * 64 + ks * 32 + (l >> 4) * 8);
;         };
;         ldchunk(0);
.LBB0_418:
	s_bfe_u32 s57, s56, 0x20003
	s_lshl_b32 s21, s56, 4
	s_and_b32 s21, s21, 0x70
	s_lshl_b32 s20, s57, 7
	s_or_b32 s20, s20, s21
	s_ashr_i32 s28, s56, 5
	v_mov_b32_e32 v220, 0xbfb8aa3b
	v_mov_b32_e32 v222, 1.0
	v_mov_b32_e32 v223, 1.0
	v_mov_b32_e32 v224, 0x3f317217
	v_mov_b32_e32 v225, 0x3f317217
	v_mov_b32_e32 v226, 0x3377d1cf
	v_mov_b32_e32 v227, 0x3377d1cf
	v_mov_b32_e32 v228, 0x3fb8aa3b
	v_mov_b32_e32 v229, 0x3fb8aa3b
	v_mov_b32_e32 v214, 0x3d800000
	v_mov_b32_e32 v215, 0x3d800000
	v_lshrrev_b32_e32 v27, 6, v249
	v_lshrrev_b32_e32 v61, 3, v160
	v_lshl_add_u32 v60, v27, 3, v61
	v_and_b32_e32 v62, 7, v160
	v_lshlrev_b32_e32 v230, 3, v160
	v_lshl_add_u32 v230, v27, 9, v230
	v_lshlrev_b32_e32 v231, 2, v62
	v_lshl_add_u32 v231, v60, 10, v231
	v_mul_u32_u24_e32 v28, 0x50, v60
	v_lshl_add_u32 v28, v62, 3, v28
	v_add_u32_e32 v28, 0x2010, v28
	v_mul_u32_u24_e32 v29, 0x50, v160
	v_add_u32_e32 v29, 0x2010, v29
	v_mul_u32_u24_e32 v30, 0x104, v62
	v_lshl_add_u32 v30, v60, 2, v30
	v_add_u32_e32 v30, 0x5010, v30
	v_mul_u32_u24_e32 v31, 0x104, v27
	v_lshl_add_u32 v31, v160, 2, v31
	v_add_u32_e32 v31, 0x5010, v31
	v_lshrrev_b32_e32 v64, 4, v160
	v_lshlrev_b32_e32 v232, 13, v72
	v_lshl_add_u32 v232, v64, 4, v232
	v_add_u32_e32 v233, 0x20000, v232
	v_lshlrev_b32_e32 v234, 8, v72
	v_lshl_add_u32 v234, v64, 3, v234
	v_add_u32_e32 v235, 0x1000, v234
	v_add_u32_e32 v65, s20, v161
	v_lshlrev_b32_e32 v65, 2, v65
	s_mov_b64 s[50:51], s[8:9]
	global_load_dwordx2 v[86:87], v65, s[50:51]
	global_load_dwordx2 v[88:89], v65, s[50:51] offset:2048
	s_add_u32 s50, s50, 0x1000
	s_addc_u32 s51, s51, 0
	global_load_dwordx2 v[90:91], v65, s[50:51]
	global_load_dwordx2 v[92:93], v65, s[50:51] offset:2048
	s_add_u32 s50, s50, 0x1000
	s_addc_u32 s51, s51, 0
	global_load_dwordx2 v[94:95], v65, s[50:51]
	global_load_dwordx2 v[96:97], v65, s[50:51] offset:2048
	s_add_u32 s50, s50, 0x1000
	s_addc_u32 s51, s51, 0
	global_load_dwordx2 v[98:99], v65, s[50:51]
	global_load_dwordx2 v[100:101], v65, s[50:51] offset:2048
	s_add_u32 s50, s50, 0x1000
	s_addc_u32 s51, s51, 0
	global_load_dwordx2 v[102:103], v65, s[50:51]
	global_load_dwordx2 v[104:105], v65, s[50:51] offset:2048
	s_add_u32 s50, s50, 0x1000
	s_addc_u32 s51, s51, 0
	global_load_dwordx2 v[106:107], v65, s[50:51]
	global_load_dwordx2 v[108:109], v65, s[50:51] offset:2048
	s_add_u32 s50, s50, 0x1000
	s_addc_u32 s51, s51, 0
	global_load_dwordx2 v[110:111], v65, s[50:51]
	global_load_dwordx2 v[112:113], v65, s[50:51] offset:2048
	s_add_u32 s50, s50, 0x1000
	s_addc_u32 s51, s51, 0
	global_load_dwordx2 v[114:115], v65, s[50:51]
	global_load_dwordx2 v[116:117], v65, s[50:51] offset:2048
	s_add_u32 s50, s50, 0x1000
	s_addc_u32 s51, s51, 0
	global_load_dwordx2 v[118:119], v65, s[18:19]
	v_readlane_b32 s26, v253, 13
	v_readlane_b32 s27, v253, 14
	v_readlane_b32 s58, v254, 26
	v_readlane_b32 s59, v254, 27
	v_readlane_b32 s34, v253, 11
	v_readlane_b32 s35, v253, 12
	v_readlane_b32 s100, v254, 28
	v_readlane_b32 s101, v254, 29
	s_lshl_b32 s52, s28, 18
	s_add_u32 s26, s26, s52
	s_addc_u32 s27, s27, 0
	s_lshl_b32 s52, s28, 22
	s_lshl_b32 s53, s20, 1
	s_add_u32 s52, s52, s53
	s_add_u32 s58, s58, s52
	s_addc_u32 s59, s59, 0
	s_lshl_b32 s52, s28, 23
	s_lshl_b32 s53, s57, 21
	s_add_u32 s52, s52, s53
	s_add_u32 s34, s34, s52
	s_addc_u32 s35, s35, 0
	s_lshl_b32 s52, s28, 8
	s_or_b32 s52, s52, s57
	s_lshl_b32 s52, s52, 16
	s_lshl_b32 s53, s21, 1
	s_add_u32 s52, s52, s53
	s_add_u32 s100, s100, s52
	s_addc_u32 s101, s101, 0
	v_mov_b32_e32 v0, 0
	v_mov_b32_e32 v1, 0
	v_mov_b32_e32 v2, 0
	v_mov_b32_e32 v3, 0
	v_mov_b32_e32 v4, 0
	v_mov_b32_e32 v5, 0
	v_mov_b32_e32 v6, 0
	v_mov_b32_e32 v7, 0
	s_barrier
	global_load_dwordx2 v[48:49], v230, s[26:27]
	global_load_dword v50, v231, s[58:59]
	s_add_u32 s26, s26, 0x1000
	s_addc_u32 s27, s27, 0
	s_add_u32 s58, s58, 0x10000
	s_addc_u32 s59, s59, 0
	global_load_dwordx2 v[52:53], v230, s[26:27]
	global_load_dword v54, v231, s[58:59]
	s_add_u32 s26, s26, 0x1000
	s_addc_u32 s27, s27, 0
	s_add_u32 s58, s58, 0x10000
	s_addc_u32 s59, s59, 0
	global_load_dwordx2 v[56:57], v230, s[26:27]
	global_load_dword v58, v231, s[58:59]
	s_add_u32 s26, s26, 0x1000
	s_addc_u32 s27, s27, 0
	s_add_u32 s58, s58, 0x10000
	s_addc_u32 s59, s59, 0
	global_load_dwordx4 v[32:35], v232, s[34:35]
	global_load_dwordx4 v[36:39], v232, s[34:35] offset:64
	global_load_dwordx4 v[40:43], v233, s[34:35]
	global_load_dwordx4 v[44:47], v233, s[34:35] offset:64
	s_add_u32 s34, s34, 0x80
	s_addc_u32 s35, s35, 0
	global_load_dwordx4 v[178:181], v232, s[34:35]
	global_load_dwordx4 v[182:185], v232, s[34:35] offset:64
	global_load_dwordx4 v[186:189], v233, s[34:35]
	global_load_dwordx4 v[190:193], v233, s[34:35] offset:64
	s_add_u32 s34, s34, 0x80
	s_addc_u32 s35, s35, 0
	s_waitcnt vmcnt(0)
	ds_write_b64 v28, v[48:49] offset:0
	ds_write_b32 v30, v50 offset:0
	s_waitcnt lgkmcnt(0)
	s_barrier
	ds_read_b128 v[8:11], v29 offset:0
	ds_read_b128 v[12:15], v29 offset:16
	ds_read_b128 v[16:19], v29 offset:32
	ds_read_b128 v[20:23], v29 offset:48
	ds_read_b32 v24, v31 offset:0
	s_mov_b32 s28, 10
; DI bf16_t f2bf(float x) { return (bf16_t)(pk2(x, 0.f) & 0xffffu); }
; DI float bf2f(unsigned x) { return __uint_as_float(x << 16); }
;     ...
;         for (int n = 0; n < 64; ++n) {
;             const int buf = n & 1;
;             f32x4 a4[4]; bf16x8 vfr[2][2];
; #pragma unroll
;             for (int q = 0; q < 4; ++q) a4[q] = a4n[q];
;             const unsigned kraw = krawn;
; #pragma unroll
;             for (int e = 0; e < 2; ++e)
; #pragma unroll
;                 for (int ks = 0; ks < 2; ++ks) vfr[e][ks] = vfrn[e][ks];
;             if (n + 1 < 64) ldchunk(n + 1);
;             float cum[2];
; #pragma unroll
;             for (int e = 0; e < 2; ++e) {
;                 float z = bb[e];
; #pragma unroll
;                 for (int q = 0; q < 4; ++q) { z += a4[q].x * wa[e][4 * q] + a4[q].y * wa[e][4 * q + 1] + a4[q].z * wa[e][4 * q + 2] + a4[q].w * wa[e][4 * q + 3]; }
;                 cum[e] = (fminf(z, 0.f) - __logf(1.f + __expf(-fabsf(z)))) * (1.f / 16.f);
;             }
; #pragma unroll
;             for (int o = 1; o < 64; o <<= 1) {
;                 const float t0 = __shfl_up(cum[0], o), t1 = __shfl_up(cum[1], o);
;                 if (l >= o) { cum[0] += t0; cum[1] += t1; }
;             }
;             const float tot0 = __shfl(cum[0], 63), tot1 = __shfl(cum[1], 63);
;             kdl[(buf * 16 + 2 * w) * 64 + l] = f2bf(bf2f(kraw & 0xffffu) * __expf(tot0 - cum[0]));
;             kdl[(buf * 16 + 2 * w + 1) * 64 + l] = f2bf(bf2f(kraw >> 16) * __expf(tot1 - cum[1]));
;             if (l == 0) { decl[buf * 16 + 2 * w] = __expf(tot0); decl[buf * 16 + 2 * w + 1] = __expf(tot1); }
;             __syncthreads();
.Lgscan_loop:
	global_load_dwordx2 v[48:49], v230, s[26:27]
	global_load_dword v50, v231, s[58:59]
	s_add_u32 s26, s26, 0x1000
	s_addc_u32 s27, s27, 0
	s_add_u32 s58, s58, 0x10000
	s_addc_u32 s59, s59, 0
	global_load_dwordx4 v[194:197], v232, s[34:35]
	global_load_dwordx4 v[198:201], v232, s[34:35] offset:64
	global_load_dwordx4 v[202:205], v233, s[34:35]
	global_load_dwordx4 v[206:209], v233, s[34:35] offset:64
	s_add_u32 s34, s34, 0x80
	s_addc_u32 s35, s35, 0
	s_waitcnt vmcnt(20)
	ds_write_b64 v28, v[52:53] offset:5120
	ds_write_b32 v30, v54 offset:2080
	s_waitcnt lgkmcnt(2)
	v_pk_fma_f32 v[64:65], v[8:9], v[86:87], v[118:119] op_sel:[0,0,0] op_sel_hi:[0,1,1]
	v_pk_mul_f32 v[66:67], v[16:17], v[102:103] op_sel:[0,0] op_sel_hi:[0,1]
	v_pk_fma_f32 v[64:65], v[8:9], v[88:89], v[64:65] op_sel:[1,0,0] op_sel_hi:[1,1,1]
	v_pk_fma_f32 v[66:67], v[16:17], v[104:105], v[66:67] op_sel:[1,0,0] op_sel_hi:[1,1,1]
	v_pk_fma_f32 v[64:65], v[10:11], v[90:91], v[64:65] op_sel:[0,0,0] op_sel_hi:[0,1,1]
	v_pk_fma_f32 v[66:67], v[18:19], v[106:107], v[66:67] op_sel:[0,0,0] op_sel_hi:[0,1,1]
	v_pk_fma_f32 v[64:65], v[10:11], v[92:93], v[64:65] op_sel:[1,0,0] op_sel_hi:[1,1,1]
	v_pk_fma_f32 v[66:67], v[18:19], v[108:109], v[66:67] op_sel:[1,0,0] op_sel_hi:[1,1,1]
	v_pk_fma_f32 v[64:65], v[12:13], v[94:95], v[64:65] op_sel:[0,0,0] op_sel_hi:[0,1,1]
	v_pk_fma_f32 v[66:67], v[20:21], v[110:111], v[66:67] op_sel:[0,0,0] op_sel_hi:[0,1,1]
	v_pk_fma_f32 v[64:65], v[12:13], v[96:97], v[64:65] op_sel:[1,0,0] op_sel_hi:[1,1,1]
	v_pk_fma_f32 v[66:67], v[20:21], v[112:113], v[66:67] op_sel:[1,0,0] op_sel_hi:[1,1,1]
	v_pk_fma_f32 v[64:65], v[14:15], v[98:99], v[64:65] op_sel:[0,0,0] op_sel_hi:[0,1,1]
	v_pk_fma_f32 v[66:67], v[22:23], v[114:115], v[66:67] op_sel:[0,0,0] op_sel_hi:[0,1,1]
	v_pk_fma_f32 v[64:65], v[14:15], v[100:101], v[64:65] op_sel:[1,0,0] op_sel_hi:[1,1,1]
	v_pk_fma_f32 v[66:67], v[22:23], v[116:117], v[66:67] op_sel:[1,0,0] op_sel_hi:[1,1,1]
	v_lshlrev_b32_e32 v148, 16, v24
	v_pk_add_f32 v[64:65], v[64:65], v[66:67]
	v_and_b32_e32 v149, 0xffff0000, v24
	v_mul_f32_e64 v68, |v64|, v220
	v_mul_f32_e64 v69, |v65|, v220
	v_exp_f32_e32 v68, v68
	v_exp_f32_e32 v69, v69
	v_min_f32_e32 v70, 0, v64
	v_min_f32_e32 v71, 0, v65
	v_pk_add_f32 v[68:69], v[68:69], v[222:223]
	s_nop 0
	v_log_f32_e32 v138, v68
	v_log_f32_e32 v139, v69
	s_nop 0
	v_pk_mul_f32 v[140:141], v[138:139], v[224:225]
	s_nop 0
	v_pk_fma_f32 v[142:143], v[138:139], v[224:225], v[140:141] neg_lo:[0,0,1] neg_hi:[0,0,1]
	s_nop 0
	v_pk_fma_f32 v[142:143], v[138:139], v[226:227], v[142:143]
	s_nop 0
	v_pk_fma_f32 v[142:143], v[138:139], v[224:225], v[142:143]
	s_nop 0
	v_pk_add_f32 v[144:145], v[70:71], v[142:143] neg_lo:[0,1] neg_hi:[0,1]
	s_nop 0
	v_pk_mul_f32 v[144:145], v[144:145], v[214:215]
	s_nop 1
	v_add_f32_dpp v144, v144, v144 row_shr:1 row_mask:0xf bank_mask:0xf
	v_add_f32_dpp v145, v145, v145 row_shr:1 row_mask:0xf bank_mask:0xf
	s_nop 0
	v_add_f32_dpp v144, v144, v144 row_shr:2 row_mask:0xf bank_mask:0xf
	v_add_f32_dpp v145, v145, v145 row_shr:2 row_mask:0xf bank_mask:0xf
	s_nop 0
	v_add_f32_dpp v144, v144, v144 row_shr:4 row_mask:0xf bank_mask:0xf
	v_add_f32_dpp v145, v145, v145 row_shr:4 row_mask:0xf bank_mask:0xf
	s_nop 0
	v_add_f32_dpp v144, v144, v144 row_shr:8 row_mask:0xf bank_mask:0xf
	v_add_f32_dpp v145, v145, v145 row_shr:8 row_mask:0xf bank_mask:0xf
	s_nop 0
	v_add_f32_dpp v144, v144, v144 row_bcast:15 row_mask:0xa bank_mask:0xf
	v_add_f32_dpp v145, v145, v145 row_bcast:15 row_mask:0xa bank_mask:0xf
	s_nop 0
	v_add_f32_dpp v144, v144, v144 row_bcast:31 row_mask:0xc bank_mask:0xf
	v_add_f32_dpp v145, v145, v145 row_bcast:31 row_mask:0xc bank_mask:0xf
	s_nop 0
	v_readlane_b32 s98, v144, 63
	v_readlane_b32 s99, v145, 63
	s_nop 1
	v_pk_add_f32 v[146:147], s[98:99], v[144:145] neg_lo:[0,1] neg_hi:[0,1]
	v_mul_f32_e64 v152, s98, v228
	v_mul_f32_e64 v153, s99, v228
	v_pk_mul_f32 v[146:147], v[146:147], v[228:229]
	v_exp_f32_e32 v152, v152
	v_exp_f32_e32 v153, v153
	v_exp_f32_e32 v146, v146
	v_exp_f32_e32 v147, v147
	s_nop 0
	v_pk_mul_f32 v[146:147], v[146:147], v[148:149]
	s_nop 0
	v_cvt_pk_bf16_f32 v150, v146, v147
	s_nop 0
	ds_write_b16 v172, v150 offset:0
	ds_write_b16_d16_hi v172, v150 offset:128
	s_and_saveexec_b64 s[20:21], vcc
	ds_write_b64 v163, v[152:153] offset:4096
	s_mov_b64 exec, s[20:21]
	s_waitcnt lgkmcnt(0)
	s_barrier
; #define MFMA16(a, b, c) __builtin_amdgcn_mfma_f32_16x16x32_bf16((a), (b), (c), 0, 0, 0)
;     ...
;         for (int n = 0; n < 64; ++n) {
;             const int buf = n & 1;
;             f32x4 a4[4]; bf16x8 vfr[2][2];
; #pragma unroll
;             for (int q = 0; q < 4; ++q) a4[q] = a4n[q];
;             const unsigned kraw = krawn;
; #pragma unroll
;             for (int e = 0; e < 2; ++e)
; #pragma unroll
;                 for (int ks = 0; ks < 2; ++ks) vfr[e][ks] = vfrn[e][ks];
;             if (n + 1 < 64) ldchunk(n + 1);
;             float cum[2];
; #pragma unroll
;             for (int e = 0; e < 2; ++e) {
;                 float z = bb[e];
; #pragma unroll
;                 for (int q = 0; q < 4; ++q) { z += a4[q].x * wa[e][4 * q] + a4[q].y * wa[e][4 * q + 1] + a4[q].z * wa[e][4 * q + 2] + a4[q].w * wa[e][4 * q + 3]; }
;                 cum[e] = (fminf(z, 0.f) - __logf(1.f + __expf(-fabsf(z)))) * (1.f / 16.f);
;             }
; #pragma unroll
;             for (int o = 1; o < 64; o <<= 1) {
;                 const float t0 = __shfl_up(cum[0], o), t1 = __shfl_up(cum[1], o);
;                 if (l >= o) { cum[0] += t0; cum[1] += t1; }
;             }
;             const float tot0 = __shfl(cum[0], 63), tot1 = __shfl(cum[1], 63);
;             kdl[(buf * 16 + 2 * w) * 64 + l] = f2bf(bf2f(kraw & 0xffffu) * __expf(tot0 - cum[0]));
;             kdl[(buf * 16 + 2 * w + 1) * 64 + l] = f2bf(bf2f(kraw >> 16) * __expf(tot1 - cum[1]));
;             if (l == 0) { decl[buf * 16 + 2 * w] = __expf(tot0); decl[buf * 16 + 2 * w + 1] = __expf(tot1); }
;             __syncthreads();
;             const f32x4 d4 = *(const f32x4*)(decl + buf * 16 + (l >> 4) * 4);
; #pragma unroll
;             for (int e = 0; e < 2; ++e) acc[e] = acc[e] * d4;
; #pragma unroll
;             for (int ks = 0; ks < 2; ++ks) {
;                 const bf16x8 af = *(const bf16x8*)(kdl + (buf * 16 + (l & 15)) * 64 + ks * 32 + (l >> 4) * 8);
; #pragma unroll
;                 for (int e = 0; e < 2; ++e) acc[e] = MFMA16(af, vfr[e][ks], acc[e]);
;             }
;             const int cidx = b * 64 + n;
; #pragma unroll
;             for (int e = 0; e < 2; ++e) {
;                 const int vv = (2 * w + e) * 16 + (l & 15);
;                 *(u32x2*)(ST + (((size_t)(cidx * 4 + hh)) * 256 + vv) * 128 + ksl * 16 + (l >> 4) * 4) = pk4(acc[e].x, acc[e].y, acc[e].z, acc[e].w);
;             }
	ds_read_b128 v[154:157], v75 offset:0
	ds_read_b128 v[240:243], v164 offset:4096
	ds_read_b128 v[236:239], v75 offset:64
	ds_read_b128 v[8:11], v29 offset:5120
	ds_read_b128 v[12:15], v29 offset:5136
	ds_read_b128 v[16:19], v29 offset:5152
	ds_read_b128 v[20:23], v29 offset:5168
	ds_read_b32 v24, v31 offset:2080
	s_waitcnt lgkmcnt(6)
	v_pk_mul_f32 v[0:1], v[0:1], v[240:241]
	v_pk_mul_f32 v[2:3], v[2:3], v[242:243]
	v_pk_mul_f32 v[4:5], v[4:5], v[240:241]
	v_pk_mul_f32 v[6:7], v[6:7], v[242:243]
	s_waitcnt vmcnt(16)
	s_nop 0
	v_mfma_f32_16x16x32_bf16 v[0:3], v[154:157], v[32:35], v[0:3]
	v_mfma_f32_16x16x32_bf16 v[4:7], v[154:157], v[40:43], v[4:7]
	s_waitcnt lgkmcnt(5)
	v_mfma_f32_16x16x32_bf16 v[0:3], v[236:239], v[36:39], v[0:3]
	v_mfma_f32_16x16x32_bf16 v[4:7], v[236:239], v[44:47], v[4:7]
	s_nop 7
	v_cvt_pk_bf16_f32 v244, v0, v1
	v_cvt_pk_bf16_f32 v245, v2, v3
	v_cvt_pk_bf16_f32 v246, v4, v5
	v_cvt_pk_bf16_f32 v247, v6, v7
	global_store_dwordx2 v234, v[244:245], s[100:101]
	global_store_dwordx2 v235, v[246:247], s[100:101]
	s_add_u32 s100, s100, 0x40000
	s_addc_u32 s101, s101, 0
	global_load_dwordx2 v[52:53], v230, s[26:27]
	global_load_dword v54, v231, s[58:59]
	s_add_u32 s26, s26, 0x1000
	s_addc_u32 s27, s27, 0
	s_add_u32 s58, s58, 0x10000
	s_addc_u32 s59, s59, 0
	global_load_dwordx4 v[32:35], v232, s[34:35]
	global_load_dwordx4 v[36:39], v232, s[34:35] offset:64
	global_load_dwordx4 v[40:43], v233, s[34:35]
	global_load_dwordx4 v[44:47], v233, s[34:35] offset:64
	s_add_u32 s34, s34, 0x80
	s_addc_u32 s35, s35, 0
	s_waitcnt vmcnt(20)
	ds_write_b64 v28, v[56:57] offset:0
	ds_write_b32 v30, v58 offset:0
	s_waitcnt lgkmcnt(2)
	v_pk_fma_f32 v[64:65], v[8:9], v[86:87], v[118:119] op_sel:[0,0,0] op_sel_hi:[0,1,1]
	v_pk_mul_f32 v[66:67], v[16:17], v[102:103] op_sel:[0,0] op_sel_hi:[0,1]
	v_pk_fma_f32 v[64:65], v[8:9], v[88:89], v[64:65] op_sel:[1,0,0] op_sel_hi:[1,1,1]
	v_pk_fma_f32 v[66:67], v[16:17], v[104:105], v[66:67] op_sel:[1,0,0] op_sel_hi:[1,1,1]
	v_pk_fma_f32 v[64:65], v[10:11], v[90:91], v[64:65] op_sel:[0,0,0] op_sel_hi:[0,1,1]
	v_pk_fma_f32 v[66:67], v[18:19], v[106:107], v[66:67] op_sel:[0,0,0] op_sel_hi:[0,1,1]
	v_pk_fma_f32 v[64:65], v[10:11], v[92:93], v[64:65] op_sel:[1,0,0] op_sel_hi:[1,1,1]
	v_pk_fma_f32 v[66:67], v[18:19], v[108:109], v[66:67] op_sel:[1,0,0] op_sel_hi:[1,1,1]
	v_pk_fma_f32 v[64:65], v[12:13], v[94:95], v[64:65] op_sel:[0,0,0] op_sel_hi:[0,1,1]
	v_pk_fma_f32 v[66:67], v[20:21], v[110:111], v[66:67] op_sel:[0,0,0] op_sel_hi:[0,1,1]
	v_pk_fma_f32 v[64:65], v[12:13], v[96:97], v[64:65] op_sel:[1,0,0] op_sel_hi:[1,1,1]
	v_pk_fma_f32 v[66:67], v[20:21], v[112:113], v[66:67] op_sel:[1,0,0] op_sel_hi:[1,1,1]
	v_pk_fma_f32 v[64:65], v[14:15], v[98:99], v[64:65] op_sel:[0,0,0] op_sel_hi:[0,1,1]
	v_pk_fma_f32 v[66:67], v[22:23], v[114:115], v[66:67] op_sel:[0,0,0] op_sel_hi:[0,1,1]
	v_pk_fma_f32 v[64:65], v[14:15], v[100:101], v[64:65] op_sel:[1,0,0] op_sel_hi:[1,1,1]
	v_pk_fma_f32 v[66:67], v[22:23], v[116:117], v[66:67] op_sel:[1,0,0] op_sel_hi:[1,1,1]
	v_lshlrev_b32_e32 v148, 16, v24
	v_pk_add_f32 v[64:65], v[64:65], v[66:67]
	v_and_b32_e32 v149, 0xffff0000, v24
	v_mul_f32_e64 v68, |v64|, v220
	v_mul_f32_e64 v69, |v65|, v220
	v_exp_f32_e32 v68, v68
	v_exp_f32_e32 v69, v69
	v_min_f32_e32 v70, 0, v64
	v_min_f32_e32 v71, 0, v65
	v_pk_add_f32 v[68:69], v[68:69], v[222:223]
	s_nop 0
	v_log_f32_e32 v138, v68
	v_log_f32_e32 v139, v69
	s_nop 0
	v_pk_mul_f32 v[140:141], v[138:139], v[224:225]
	s_nop 0
	v_pk_fma_f32 v[142:143], v[138:139], v[224:225], v[140:141] neg_lo:[0,0,1] neg_hi:[0,0,1]
	s_nop 0
	v_pk_fma_f32 v[142:143], v[138:139], v[226:227], v[142:143]
	s_nop 0
	v_pk_fma_f32 v[142:143], v[138:139], v[224:225], v[142:143]
	s_nop 0
	v_pk_add_f32 v[144:145], v[70:71], v[142:143] neg_lo:[0,1] neg_hi:[0,1]
	s_nop 0
	v_pk_mul_f32 v[144:145], v[144:145], v[214:215]
	s_nop 1
	v_add_f32_dpp v144, v144, v144 row_shr:1 row_mask:0xf bank_mask:0xf
	v_add_f32_dpp v145, v145, v145 row_shr:1 row_mask:0xf bank_mask:0xf
	s_nop 0
	v_add_f32_dpp v144, v144, v144 row_shr:2 row_mask:0xf bank_mask:0xf
	v_add_f32_dpp v145, v145, v145 row_shr:2 row_mask:0xf bank_mask:0xf
	s_nop 0
	v_add_f32_dpp v144, v144, v144 row_shr:4 row_mask:0xf bank_mask:0xf
	v_add_f32_dpp v145, v145, v145 row_shr:4 row_mask:0xf bank_mask:0xf
	s_nop 0
	v_add_f32_dpp v144, v144, v144 row_shr:8 row_mask:0xf bank_mask:0xf
	v_add_f32_dpp v145, v145, v145 row_shr:8 row_mask:0xf bank_mask:0xf
	s_nop 0
	v_add_f32_dpp v144, v144, v144 row_bcast:15 row_mask:0xa bank_mask:0xf
	v_add_f32_dpp v145, v145, v145 row_bcast:15 row_mask:0xa bank_mask:0xf
	s_nop 0
	v_add_f32_dpp v144, v144, v144 row_bcast:31 row_mask:0xc bank_mask:0xf
	v_add_f32_dpp v145, v145, v145 row_bcast:31 row_mask:0xc bank_mask:0xf
	s_nop 0
	v_readlane_b32 s98, v144, 63
	v_readlane_b32 s99, v145, 63
	s_nop 1
	v_pk_add_f32 v[146:147], s[98:99], v[144:145] neg_lo:[0,1] neg_hi:[0,1]
	v_mul_f32_e64 v152, s98, v228
	v_mul_f32_e64 v153, s99, v228
	v_pk_mul_f32 v[146:147], v[146:147], v[228:229]
	v_exp_f32_e32 v152, v152
	v_exp_f32_e32 v153, v153
	v_exp_f32_e32 v146, v146
	v_exp_f32_e32 v147, v147
	s_nop 0
	v_pk_mul_f32 v[146:147], v[146:147], v[148:149]
	s_nop 0
	v_cvt_pk_bf16_f32 v150, v146, v147
	s_nop 0
	ds_write_b16 v172, v150 offset:2048
	ds_write_b16_d16_hi v172, v150 offset:2176
	s_and_saveexec_b64 s[20:21], vcc
	ds_write_b64 v163, v[152:153] offset:4160
	s_mov_b64 exec, s[20:21]
	s_waitcnt lgkmcnt(0)
	s_barrier
; #define MFMA16(a, b, c) __builtin_amdgcn_mfma_f32_16x16x32_bf16((a), (b), (c), 0, 0, 0)
;     ...
;         for (int n = 0; n < 64; ++n) {
;             const int buf = n & 1;
;             f32x4 a4[4]; bf16x8 vfr[2][2];
; #pragma unroll
;             for (int q = 0; q < 4; ++q) a4[q] = a4n[q];
;             const unsigned kraw = krawn;
; #pragma unroll
;             for (int e = 0; e < 2; ++e)
; #pragma unroll
;                 for (int ks = 0; ks < 2; ++ks) vfr[e][ks] = vfrn[e][ks];
;             if (n + 1 < 64) ldchunk(n + 1);
;             float cum[2];
; #pragma unroll
;             for (int e = 0; e < 2; ++e) {
;                 float z = bb[e];
; #pragma unroll
;                 for (int q = 0; q < 4; ++q) { z += a4[q].x * wa[e][4 * q] + a4[q].y * wa[e][4 * q + 1] + a4[q].z * wa[e][4 * q + 2] + a4[q].w * wa[e][4 * q + 3]; }
;                 cum[e] = (fminf(z, 0.f) - __logf(1.f + __expf(-fabsf(z)))) * (1.f / 16.f);
;             }
; #pragma unroll
;             for (int o = 1; o < 64; o <<= 1) {
;                 const float t0 = __shfl_up(cum[0], o), t1 = __shfl_up(cum[1], o);
;                 if (l >= o) { cum[0] += t0; cum[1] += t1; }
;             }
;             const float tot0 = __shfl(cum[0], 63), tot1 = __shfl(cum[1], 63);
;             kdl[(buf * 16 + 2 * w) * 64 + l] = f2bf(bf2f(kraw & 0xffffu) * __expf(tot0 - cum[0]));
;             kdl[(buf * 16 + 2 * w + 1) * 64 + l] = f2bf(bf2f(kraw >> 16) * __expf(tot1 - cum[1]));
;             if (l == 0) { decl[buf * 16 + 2 * w] = __expf(tot0); decl[buf * 16 + 2 * w + 1] = __expf(tot1); }
;             __syncthreads();
;             const f32x4 d4 = *(const f32x4*)(decl + buf * 16 + (l >> 4) * 4);
; #pragma unroll
;             for (int e = 0; e < 2; ++e) acc[e] = acc[e] * d4;
; #pragma unroll
;             for (int ks = 0; ks < 2; ++ks) {
;                 const bf16x8 af = *(const bf16x8*)(kdl + (buf * 16 + (l & 15)) * 64 + ks * 32 + (l >> 4) * 8);
; #pragma unroll
;                 for (int e = 0; e < 2; ++e) acc[e] = MFMA16(af, vfr[e][ks], acc[e]);
;             }
;             const int cidx = b * 64 + n;
; #pragma unroll
;             for (int e = 0; e < 2; ++e) {
;                 const int vv = (2 * w + e) * 16 + (l & 15);
;                 *(u32x2*)(ST + (((size_t)(cidx * 4 + hh)) * 256 + vv) * 128 + ksl * 16 + (l >> 4) * 4) = pk4(acc[e].x, acc[e].y, acc[e].z, acc[e].w);
;             }
	ds_read_b128 v[154:157], v75 offset:2048
	ds_read_b128 v[240:243], v164 offset:4160
	ds_read_b128 v[236:239], v75 offset:2112
	ds_read_b128 v[8:11], v29 offset:0
	ds_read_b128 v[12:15], v29 offset:16
	ds_read_b128 v[16:19], v29 offset:32
	ds_read_b128 v[20:23], v29 offset:48
	ds_read_b32 v24, v31 offset:0
	s_waitcnt lgkmcnt(6)
	v_pk_mul_f32 v[0:1], v[0:1], v[240:241]
	v_pk_mul_f32 v[2:3], v[2:3], v[242:243]
	v_pk_mul_f32 v[4:5], v[4:5], v[240:241]
	v_pk_mul_f32 v[6:7], v[6:7], v[242:243]
	s_waitcnt vmcnt(16)
	s_nop 0
	v_mfma_f32_16x16x32_bf16 v[0:3], v[154:157], v[178:181], v[0:3]
	v_mfma_f32_16x16x32_bf16 v[4:7], v[154:157], v[186:189], v[4:7]
	s_waitcnt lgkmcnt(5)
	v_mfma_f32_16x16x32_bf16 v[0:3], v[236:239], v[182:185], v[0:3]
	v_mfma_f32_16x16x32_bf16 v[4:7], v[236:239], v[190:193], v[4:7]
	s_nop 7
	v_cvt_pk_bf16_f32 v244, v0, v1
	v_cvt_pk_bf16_f32 v245, v2, v3
	v_cvt_pk_bf16_f32 v246, v4, v5
	v_cvt_pk_bf16_f32 v247, v6, v7
	global_store_dwordx2 v234, v[244:245], s[100:101]
	global_store_dwordx2 v235, v[246:247], s[100:101]
	s_add_u32 s100, s100, 0x40000
	s_addc_u32 s101, s101, 0
	global_load_dwordx2 v[56:57], v230, s[26:27]
	global_load_dword v58, v231, s[58:59]
	s_add_u32 s26, s26, 0x1000
	s_addc_u32 s27, s27, 0
	s_add_u32 s58, s58, 0x10000
	s_addc_u32 s59, s59, 0
	global_load_dwordx4 v[178:181], v232, s[34:35]
	global_load_dwordx4 v[182:185], v232, s[34:35] offset:64
	global_load_dwordx4 v[186:189], v233, s[34:35]
	global_load_dwordx4 v[190:193], v233, s[34:35] offset:64
	s_add_u32 s34, s34, 0x80
	s_addc_u32 s35, s35, 0
	s_waitcnt vmcnt(20)
	ds_write_b64 v28, v[48:49] offset:5120
	ds_write_b32 v30, v50 offset:2080
	s_waitcnt lgkmcnt(2)
	v_pk_fma_f32 v[64:65], v[8:9], v[86:87], v[118:119] op_sel:[0,0,0] op_sel_hi:[0,1,1]
	v_pk_mul_f32 v[66:67], v[16:17], v[102:103] op_sel:[0,0] op_sel_hi:[0,1]
	v_pk_fma_f32 v[64:65], v[8:9], v[88:89], v[64:65] op_sel:[1,0,0] op_sel_hi:[1,1,1]
	v_pk_fma_f32 v[66:67], v[16:17], v[104:105], v[66:67] op_sel:[1,0,0] op_sel_hi:[1,1,1]
	v_pk_fma_f32 v[64:65], v[10:11], v[90:91], v[64:65] op_sel:[0,0,0] op_sel_hi:[0,1,1]
	v_pk_fma_f32 v[66:67], v[18:19], v[106:107], v[66:67] op_sel:[0,0,0] op_sel_hi:[0,1,1]
	v_pk_fma_f32 v[64:65], v[10:11], v[92:93], v[64:65] op_sel:[1,0,0] op_sel_hi:[1,1,1]
	v_pk_fma_f32 v[66:67], v[18:19], v[108:109], v[66:67] op_sel:[1,0,0] op_sel_hi:[1,1,1]
	v_pk_fma_f32 v[64:65], v[12:13], v[94:95], v[64:65] op_sel:[0,0,0] op_sel_hi:[0,1,1]
	v_pk_fma_f32 v[66:67], v[20:21], v[110:111], v[66:67] op_sel:[0,0,0] op_sel_hi:[0,1,1]
	v_pk_fma_f32 v[64:65], v[12:13], v[96:97], v[64:65] op_sel:[1,0,0] op_sel_hi:[1,1,1]
	v_pk_fma_f32 v[66:67], v[20:21], v[112:113], v[66:67] op_sel:[1,0,0] op_sel_hi:[1,1,1]
	v_pk_fma_f32 v[64:65], v[14:15], v[98:99], v[64:65] op_sel:[0,0,0] op_sel_hi:[0,1,1]
	v_pk_fma_f32 v[66:67], v[22:23], v[114:115], v[66:67] op_sel:[0,0,0] op_sel_hi:[0,1,1]
	v_pk_fma_f32 v[64:65], v[14:15], v[100:101], v[64:65] op_sel:[1,0,0] op_sel_hi:[1,1,1]
	v_pk_fma_f32 v[66:67], v[22:23], v[116:117], v[66:67] op_sel:[1,0,0] op_sel_hi:[1,1,1]
	v_lshlrev_b32_e32 v148, 16, v24
	v_pk_add_f32 v[64:65], v[64:65], v[66:67]
	v_and_b32_e32 v149, 0xffff0000, v24
	v_mul_f32_e64 v68, |v64|, v220
	v_mul_f32_e64 v69, |v65|, v220
	v_exp_f32_e32 v68, v68
	v_exp_f32_e32 v69, v69
	v_min_f32_e32 v70, 0, v64
	v_min_f32_e32 v71, 0, v65
	v_pk_add_f32 v[68:69], v[68:69], v[222:223]
	s_nop 0
	v_log_f32_e32 v138, v68
	v_log_f32_e32 v139, v69
	s_nop 0
	v_pk_mul_f32 v[140:141], v[138:139], v[224:225]
	s_nop 0
	v_pk_fma_f32 v[142:143], v[138:139], v[224:225], v[140:141] neg_lo:[0,0,1] neg_hi:[0,0,1]
	s_nop 0
	v_pk_fma_f32 v[142:143], v[138:139], v[226:227], v[142:143]
	s_nop 0
	v_pk_fma_f32 v[142:143], v[138:139], v[224:225], v[142:143]
	s_nop 0
	v_pk_add_f32 v[144:145], v[70:71], v[142:143] neg_lo:[0,1] neg_hi:[0,1]
	s_nop 0
	v_pk_mul_f32 v[144:145], v[144:145], v[214:215]
	s_nop 1
	v_add_f32_dpp v144, v144, v144 row_shr:1 row_mask:0xf bank_mask:0xf
	v_add_f32_dpp v145, v145, v145 row_shr:1 row_mask:0xf bank_mask:0xf
	s_nop 0
	v_add_f32_dpp v144, v144, v144 row_shr:2 row_mask:0xf bank_mask:0xf
	v_add_f32_dpp v145, v145, v145 row_shr:2 row_mask:0xf bank_mask:0xf
	s_nop 0
	v_add_f32_dpp v144, v144, v144 row_shr:4 row_mask:0xf bank_mask:0xf
	v_add_f32_dpp v145, v145, v145 row_shr:4 row_mask:0xf bank_mask:0xf
	s_nop 0
	v_add_f32_dpp v144, v144, v144 row_shr:8 row_mask:0xf bank_mask:0xf
	v_add_f32_dpp v145, v145, v145 row_shr:8 row_mask:0xf bank_mask:0xf
	s_nop 0
	v_add_f32_dpp v144, v144, v144 row_bcast:15 row_mask:0xa bank_mask:0xf
	v_add_f32_dpp v145, v145, v145 row_bcast:15 row_mask:0xa bank_mask:0xf
	s_nop 0
	v_add_f32_dpp v144, v144, v144 row_bcast:31 row_mask:0xc bank_mask:0xf
	v_add_f32_dpp v145, v145, v145 row_bcast:31 row_mask:0xc bank_mask:0xf
	s_nop 0
	v_readlane_b32 s98, v144, 63
	v_readlane_b32 s99, v145, 63
	s_nop 1
	v_pk_add_f32 v[146:147], s[98:99], v[144:145] neg_lo:[0,1] neg_hi:[0,1]
	v_mul_f32_e64 v152, s98, v228
	v_mul_f32_e64 v153, s99, v228
	v_pk_mul_f32 v[146:147], v[146:147], v[228:229]
	v_exp_f32_e32 v152, v152
	v_exp_f32_e32 v153, v153
	v_exp_f32_e32 v146, v146
	v_exp_f32_e32 v147, v147
	s_nop 0
	v_pk_mul_f32 v[146:147], v[146:147], v[148:149]
	s_nop 0
	v_cvt_pk_bf16_f32 v150, v146, v147
	s_nop 0
	ds_write_b16 v172, v150 offset:0
	ds_write_b16_d16_hi v172, v150 offset:128
	s_and_saveexec_b64 s[20:21], vcc
	ds_write_b64 v163, v[152:153] offset:4096
	s_mov_b64 exec, s[20:21]
	s_waitcnt lgkmcnt(0)
	s_barrier
; #define MFMA16(a, b, c) __builtin_amdgcn_mfma_f32_16x16x32_bf16((a), (b), (c), 0, 0, 0)
;     ...
;         for (int n = 0; n < 64; ++n) {
;             const int buf = n & 1;
;             f32x4 a4[4]; bf16x8 vfr[2][2];
; #pragma unroll
;             for (int q = 0; q < 4; ++q) a4[q] = a4n[q];
;             const unsigned kraw = krawn;
; #pragma unroll
;             for (int e = 0; e < 2; ++e)
; #pragma unroll
;                 for (int ks = 0; ks < 2; ++ks) vfr[e][ks] = vfrn[e][ks];
;             if (n + 1 < 64) ldchunk(n + 1);
;             float cum[2];
; #pragma unroll
;             for (int e = 0; e < 2; ++e) {
;                 float z = bb[e];
; #pragma unroll
;                 for (int q = 0; q < 4; ++q) { z += a4[q].x * wa[e][4 * q] + a4[q].y * wa[e][4 * q + 1] + a4[q].z * wa[e][4 * q + 2] + a4[q].w * wa[e][4 * q + 3]; }
;                 cum[e] = (fminf(z, 0.f) - __logf(1.f + __expf(-fabsf(z)))) * (1.f / 16.f);
;             }
; #pragma unroll
;             for (int o = 1; o < 64; o <<= 1) {
;                 const float t0 = __shfl_up(cum[0], o), t1 = __shfl_up(cum[1], o);
;                 if (l >= o) { cum[0] += t0; cum[1] += t1; }
;             }
;             const float tot0 = __shfl(cum[0], 63), tot1 = __shfl(cum[1], 63);
;             kdl[(buf * 16 + 2 * w) * 64 + l] = f2bf(bf2f(kraw & 0xffffu) * __expf(tot0 - cum[0]));
;             kdl[(buf * 16 + 2 * w + 1) * 64 + l] = f2bf(bf2f(kraw >> 16) * __expf(tot1 - cum[1]));
;             if (l == 0) { decl[buf * 16 + 2 * w] = __expf(tot0); decl[buf * 16 + 2 * w + 1] = __expf(tot1); }
;             __syncthreads();
;             const f32x4 d4 = *(const f32x4*)(decl + buf * 16 + (l >> 4) * 4);
; #pragma unroll
;             for (int e = 0; e < 2; ++e) acc[e] = acc[e] * d4;
; #pragma unroll
;             for (int ks = 0; ks < 2; ++ks) {
;                 const bf16x8 af = *(const bf16x8*)(kdl + (buf * 16 + (l & 15)) * 64 + ks * 32 + (l >> 4) * 8);
; #pragma unroll
;                 for (int e = 0; e < 2; ++e) acc[e] = MFMA16(af, vfr[e][ks], acc[e]);
;             }
;             const int cidx = b * 64 + n;
; #pragma unroll
;             for (int e = 0; e < 2; ++e) {
;                 const int vv = (2 * w + e) * 16 + (l & 15);
;                 *(u32x2*)(ST + (((size_t)(cidx * 4 + hh)) * 256 + vv) * 128 + ksl * 16 + (l >> 4) * 4) = pk4(acc[e].x, acc[e].y, acc[e].z, acc[e].w);
;             }
	ds_read_b128 v[154:157], v75 offset:0
	ds_read_b128 v[240:243], v164 offset:4096
	ds_read_b128 v[236:239], v75 offset:64
	ds_read_b128 v[8:11], v29 offset:5120
	ds_read_b128 v[12:15], v29 offset:5136
	ds_read_b128 v[16:19], v29 offset:5152
	ds_read_b128 v[20:23], v29 offset:5168
	ds_read_b32 v24, v31 offset:2080
	s_waitcnt lgkmcnt(6)
	v_pk_mul_f32 v[0:1], v[0:1], v[240:241]
	v_pk_mul_f32 v[2:3], v[2:3], v[242:243]
	v_pk_mul_f32 v[4:5], v[4:5], v[240:241]
	v_pk_mul_f32 v[6:7], v[6:7], v[242:243]
	s_waitcnt vmcnt(16)
	s_nop 0
	v_mfma_f32_16x16x32_bf16 v[0:3], v[154:157], v[194:197], v[0:3]
	v_mfma_f32_16x16x32_bf16 v[4:7], v[154:157], v[202:205], v[4:7]
	s_waitcnt lgkmcnt(5)
	v_mfma_f32_16x16x32_bf16 v[0:3], v[236:239], v[198:201], v[0:3]
	v_mfma_f32_16x16x32_bf16 v[4:7], v[236:239], v[206:209], v[4:7]
	s_nop 7
	v_cvt_pk_bf16_f32 v244, v0, v1
	v_cvt_pk_bf16_f32 v245, v2, v3
	v_cvt_pk_bf16_f32 v246, v4, v5
	v_cvt_pk_bf16_f32 v247, v6, v7
	global_store_dwordx2 v234, v[244:245], s[100:101]
	global_store_dwordx2 v235, v[246:247], s[100:101]
	s_add_u32 s100, s100, 0x40000
	s_addc_u32 s101, s101, 0
	global_load_dwordx2 v[48:49], v230, s[26:27]
	global_load_dword v50, v231, s[58:59]
	s_add_u32 s26, s26, 0x1000
	s_addc_u32 s27, s27, 0
	s_add_u32 s58, s58, 0x10000
	s_addc_u32 s59, s59, 0
	global_load_dwordx4 v[194:197], v232, s[34:35]
	global_load_dwordx4 v[198:201], v232, s[34:35] offset:64
	global_load_dwordx4 v[202:205], v233, s[34:35]
	global_load_dwordx4 v[206:209], v233, s[34:35] offset:64
	s_add_u32 s34, s34, 0x80
	s_addc_u32 s35, s35, 0
	s_waitcnt vmcnt(20)
	ds_write_b64 v28, v[52:53] offset:0
	ds_write_b32 v30, v54 offset:0
	s_waitcnt lgkmcnt(2)
	v_pk_fma_f32 v[64:65], v[8:9], v[86:87], v[118:119] op_sel:[0,0,0] op_sel_hi:[0,1,1]
	v_pk_mul_f32 v[66:67], v[16:17], v[102:103] op_sel:[0,0] op_sel_hi:[0,1]
	v_pk_fma_f32 v[64:65], v[8:9], v[88:89], v[64:65] op_sel:[1,0,0] op_sel_hi:[1,1,1]
	v_pk_fma_f32 v[66:67], v[16:17], v[104:105], v[66:67] op_sel:[1,0,0] op_sel_hi:[1,1,1]
	v_pk_fma_f32 v[64:65], v[10:11], v[90:91], v[64:65] op_sel:[0,0,0] op_sel_hi:[0,1,1]
	v_pk_fma_f32 v[66:67], v[18:19], v[106:107], v[66:67] op_sel:[0,0,0] op_sel_hi:[0,1,1]
	v_pk_fma_f32 v[64:65], v[10:11], v[92:93], v[64:65] op_sel:[1,0,0] op_sel_hi:[1,1,1]
	v_pk_fma_f32 v[66:67], v[18:19], v[108:109], v[66:67] op_sel:[1,0,0] op_sel_hi:[1,1,1]
	v_pk_fma_f32 v[64:65], v[12:13], v[94:95], v[64:65] op_sel:[0,0,0] op_sel_hi:[0,1,1]
	v_pk_fma_f32 v[66:67], v[20:21], v[110:111], v[66:67] op_sel:[0,0,0] op_sel_hi:[0,1,1]
	v_pk_fma_f32 v[64:65], v[12:13], v[96:97], v[64:65] op_sel:[1,0,0] op_sel_hi:[1,1,1]
	v_pk_fma_f32 v[66:67], v[20:21], v[112:113], v[66:67] op_sel:[1,0,0] op_sel_hi:[1,1,1]
	v_pk_fma_f32 v[64:65], v[14:15], v[98:99], v[64:65] op_sel:[0,0,0] op_sel_hi:[0,1,1]
	v_pk_fma_f32 v[66:67], v[22:23], v[114:115], v[66:67] op_sel:[0,0,0] op_sel_hi:[0,1,1]
	v_pk_fma_f32 v[64:65], v[14:15], v[100:101], v[64:65] op_sel:[1,0,0] op_sel_hi:[1,1,1]
	v_pk_fma_f32 v[66:67], v[22:23], v[116:117], v[66:67] op_sel:[1,0,0] op_sel_hi:[1,1,1]
	v_lshlrev_b32_e32 v148, 16, v24
	v_pk_add_f32 v[64:65], v[64:65], v[66:67]
	v_and_b32_e32 v149, 0xffff0000, v24
	v_mul_f32_e64 v68, |v64|, v220
	v_mul_f32_e64 v69, |v65|, v220
	v_exp_f32_e32 v68, v68
	v_exp_f32_e32 v69, v69
	v_min_f32_e32 v70, 0, v64
	v_min_f32_e32 v71, 0, v65
	v_pk_add_f32 v[68:69], v[68:69], v[222:223]
	s_nop 0
	v_log_f32_e32 v138, v68
	v_log_f32_e32 v139, v69
	s_nop 0
	v_pk_mul_f32 v[140:141], v[138:139], v[224:225]
	s_nop 0
	v_pk_fma_f32 v[142:143], v[138:139], v[224:225], v[140:141] neg_lo:[0,0,1] neg_hi:[0,0,1]
	s_nop 0
	v_pk_fma_f32 v[142:143], v[138:139], v[226:227], v[142:143]
	s_nop 0
	v_pk_fma_f32 v[142:143], v[138:139], v[224:225], v[142:143]
	s_nop 0
	v_pk_add_f32 v[144:145], v[70:71], v[142:143] neg_lo:[0,1] neg_hi:[0,1]
	s_nop 0
	v_pk_mul_f32 v[144:145], v[144:145], v[214:215]
	s_nop 1
	v_add_f32_dpp v144, v144, v144 row_shr:1 row_mask:0xf bank_mask:0xf
	v_add_f32_dpp v145, v145, v145 row_shr:1 row_mask:0xf bank_mask:0xf
	s_nop 0
	v_add_f32_dpp v144, v144, v144 row_shr:2 row_mask:0xf bank_mask:0xf
	v_add_f32_dpp v145, v145, v145 row_shr:2 row_mask:0xf bank_mask:0xf
	s_nop 0
	v_add_f32_dpp v144, v144, v144 row_shr:4 row_mask:0xf bank_mask:0xf
	v_add_f32_dpp v145, v145, v145 row_shr:4 row_mask:0xf bank_mask:0xf
	s_nop 0
	v_add_f32_dpp v144, v144, v144 row_shr:8 row_mask:0xf bank_mask:0xf
	v_add_f32_dpp v145, v145, v145 row_shr:8 row_mask:0xf bank_mask:0xf
	s_nop 0
	v_add_f32_dpp v144, v144, v144 row_bcast:15 row_mask:0xa bank_mask:0xf
	v_add_f32_dpp v145, v145, v145 row_bcast:15 row_mask:0xa bank_mask:0xf
	s_nop 0
	v_add_f32_dpp v144, v144, v144 row_bcast:31 row_mask:0xc bank_mask:0xf
	v_add_f32_dpp v145, v145, v145 row_bcast:31 row_mask:0xc bank_mask:0xf
	s_nop 0
	v_readlane_b32 s98, v144, 63
	v_readlane_b32 s99, v145, 63
	s_nop 1
	v_pk_add_f32 v[146:147], s[98:99], v[144:145] neg_lo:[0,1] neg_hi:[0,1]
	v_mul_f32_e64 v152, s98, v228
	v_mul_f32_e64 v153, s99, v228
	v_pk_mul_f32 v[146:147], v[146:147], v[228:229]
	v_exp_f32_e32 v152, v152
	v_exp_f32_e32 v153, v153
	v_exp_f32_e32 v146, v146
	v_exp_f32_e32 v147, v147
	s_nop 0
	v_pk_mul_f32 v[146:147], v[146:147], v[148:149]
	s_nop 0
	v_cvt_pk_bf16_f32 v150, v146, v147
	s_nop 0
	ds_write_b16 v172, v150 offset:2048
	ds_write_b16_d16_hi v172, v150 offset:2176
	s_and_saveexec_b64 s[20:21], vcc
	ds_write_b64 v163, v[152:153] offset:4160
	s_mov_b64 exec, s[20:21]
	s_waitcnt lgkmcnt(0)
	s_barrier
; #define MFMA16(a, b, c) __builtin_amdgcn_mfma_f32_16x16x32_bf16((a), (b), (c), 0, 0, 0)
;     ...
;         for (int n = 0; n < 64; ++n) {
;             const int buf = n & 1;
;             f32x4 a4[4]; bf16x8 vfr[2][2];
; #pragma unroll
;             for (int q = 0; q < 4; ++q) a4[q] = a4n[q];
;             const unsigned kraw = krawn;
; #pragma unroll
;             for (int e = 0; e < 2; ++e)
; #pragma unroll
;                 for (int ks = 0; ks < 2; ++ks) vfr[e][ks] = vfrn[e][ks];
;             if (n + 1 < 64) ldchunk(n + 1);
;             float cum[2];
; #pragma unroll
;             for (int e = 0; e < 2; ++e) {
;                 float z = bb[e];
; #pragma unroll
;                 for (int q = 0; q < 4; ++q) { z += a4[q].x * wa[e][4 * q] + a4[q].y * wa[e][4 * q + 1] + a4[q].z * wa[e][4 * q + 2] + a4[q].w * wa[e][4 * q + 3]; }
;                 cum[e] = (fminf(z, 0.f) - __logf(1.f + __expf(-fabsf(z)))) * (1.f / 16.f);
;             }
; #pragma unroll
;             for (int o = 1; o < 64; o <<= 1) {
;                 const float t0 = __shfl_up(cum[0], o), t1 = __shfl_up(cum[1], o);
;                 if (l >= o) { cum[0] += t0; cum[1] += t1; }
;             }
;             const float tot0 = __shfl(cum[0], 63), tot1 = __shfl(cum[1], 63);
;             kdl[(buf * 16 + 2 * w) * 64 + l] = f2bf(bf2f(kraw & 0xffffu) * __expf(tot0 - cum[0]));
;             kdl[(buf * 16 + 2 * w + 1) * 64 + l] = f2bf(bf2f(kraw >> 16) * __expf(tot1 - cum[1]));
;             if (l == 0) { decl[buf * 16 + 2 * w] = __expf(tot0); decl[buf * 16 + 2 * w + 1] = __expf(tot1); }
;             __syncthreads();
;             const f32x4 d4 = *(const f32x4*)(decl + buf * 16 + (l >> 4) * 4);
; #pragma unroll
;             for (int e = 0; e < 2; ++e) acc[e] = acc[e] * d4;
; #pragma unroll
;             for (int ks = 0; ks < 2; ++ks) {
;                 const bf16x8 af = *(const bf16x8*)(kdl + (buf * 16 + (l & 15)) * 64 + ks * 32 + (l >> 4) * 8);
; #pragma unroll
;                 for (int e = 0; e < 2; ++e) acc[e] = MFMA16(af, vfr[e][ks], acc[e]);
;             }
;             const int cidx = b * 64 + n;
; #pragma unroll
;             for (int e = 0; e < 2; ++e) {
;                 const int vv = (2 * w + e) * 16 + (l & 15);
;                 *(u32x2*)(ST + (((size_t)(cidx * 4 + hh)) * 256 + vv) * 128 + ksl * 16 + (l >> 4) * 4) = pk4(acc[e].x, acc[e].y, acc[e].z, acc[e].w);
;             }
	ds_read_b128 v[154:157], v75 offset:2048
	ds_read_b128 v[240:243], v164 offset:4160
	ds_read_b128 v[236:239], v75 offset:2112
	ds_read_b128 v[8:11], v29 offset:0
	ds_read_b128 v[12:15], v29 offset:16
	ds_read_b128 v[16:19], v29 offset:32
	ds_read_b128 v[20:23], v29 offset:48
	ds_read_b32 v24, v31 offset:0
	s_waitcnt lgkmcnt(6)
	v_pk_mul_f32 v[0:1], v[0:1], v[240:241]
	v_pk_mul_f32 v[2:3], v[2:3], v[242:243]
	v_pk_mul_f32 v[4:5], v[4:5], v[240:241]
	v_pk_mul_f32 v[6:7], v[6:7], v[242:243]
	s_waitcnt vmcnt(16)
	s_nop 0
	v_mfma_f32_16x16x32_bf16 v[0:3], v[154:157], v[32:35], v[0:3]
	v_mfma_f32_16x16x32_bf16 v[4:7], v[154:157], v[40:43], v[4:7]
	s_waitcnt lgkmcnt(5)
	v_mfma_f32_16x16x32_bf16 v[0:3], v[236:239], v[36:39], v[0:3]
	v_mfma_f32_16x16x32_bf16 v[4:7], v[236:239], v[44:47], v[4:7]
	s_nop 7
	v_cvt_pk_bf16_f32 v244, v0, v1
	v_cvt_pk_bf16_f32 v245, v2, v3
	v_cvt_pk_bf16_f32 v246, v4, v5
	v_cvt_pk_bf16_f32 v247, v6, v7
	global_store_dwordx2 v234, v[244:245], s[100:101]
	global_store_dwordx2 v235, v[246:247], s[100:101]
	s_add_u32 s100, s100, 0x40000
	s_addc_u32 s101, s101, 0
	global_load_dwordx2 v[52:53], v230, s[26:27]
	global_load_dword v54, v231, s[58:59]
	s_add_u32 s26, s26, 0x1000
	s_addc_u32 s27, s27, 0
	s_add_u32 s58, s58, 0x10000
	s_addc_u32 s59, s59, 0
	global_load_dwordx4 v[32:35], v232, s[34:35]
	global_load_dwordx4 v[36:39], v232, s[34:35] offset:64
	global_load_dwordx4 v[40:43], v233, s[34:35]
	global_load_dwordx4 v[44:47], v233, s[34:35] offset:64
	s_add_u32 s34, s34, 0x80
	s_addc_u32 s35, s35, 0
	s_waitcnt vmcnt(20)
	ds_write_b64 v28, v[56:57] offset:5120
	ds_write_b32 v30, v58 offset:2080
	s_waitcnt lgkmcnt(2)
	v_pk_fma_f32 v[64:65], v[8:9], v[86:87], v[118:119] op_sel:[0,0,0] op_sel_hi:[0,1,1]
	v_pk_mul_f32 v[66:67], v[16:17], v[102:103] op_sel:[0,0] op_sel_hi:[0,1]
	v_pk_fma_f32 v[64:65], v[8:9], v[88:89], v[64:65] op_sel:[1,0,0] op_sel_hi:[1,1,1]
	v_pk_fma_f32 v[66:67], v[16:17], v[104:105], v[66:67] op_sel:[1,0,0] op_sel_hi:[1,1,1]
	v_pk_fma_f32 v[64:65], v[10:11], v[90:91], v[64:65] op_sel:[0,0,0] op_sel_hi:[0,1,1]
	v_pk_fma_f32 v[66:67], v[18:19], v[106:107], v[66:67] op_sel:[0,0,0] op_sel_hi:[0,1,1]
	v_pk_fma_f32 v[64:65], v[10:11], v[92:93], v[64:65] op_sel:[1,0,0] op_sel_hi:[1,1,1]
	v_pk_fma_f32 v[66:67], v[18:19], v[108:109], v[66:67] op_sel:[1,0,0] op_sel_hi:[1,1,1]
	v_pk_fma_f32 v[64:65], v[12:13], v[94:95], v[64:65] op_sel:[0,0,0] op_sel_hi:[0,1,1]
	v_pk_fma_f32 v[66:67], v[20:21], v[110:111], v[66:67] op_sel:[0,0,0] op_sel_hi:[0,1,1]
	v_pk_fma_f32 v[64:65], v[12:13], v[96:97], v[64:65] op_sel:[1,0,0] op_sel_hi:[1,1,1]
	v_pk_fma_f32 v[66:67], v[20:21], v[112:113], v[66:67] op_sel:[1,0,0] op_sel_hi:[1,1,1]
	v_pk_fma_f32 v[64:65], v[14:15], v[98:99], v[64:65] op_sel:[0,0,0] op_sel_hi:[0,1,1]
	v_pk_fma_f32 v[66:67], v[22:23], v[114:115], v[66:67] op_sel:[0,0,0] op_sel_hi:[0,1,1]
	v_pk_fma_f32 v[64:65], v[14:15], v[100:101], v[64:65] op_sel:[1,0,0] op_sel_hi:[1,1,1]
	v_pk_fma_f32 v[66:67], v[22:23], v[116:117], v[66:67] op_sel:[1,0,0] op_sel_hi:[1,1,1]
	v_lshlrev_b32_e32 v148, 16, v24
	v_pk_add_f32 v[64:65], v[64:65], v[66:67]
	v_and_b32_e32 v149, 0xffff0000, v24
	v_mul_f32_e64 v68, |v64|, v220
	v_mul_f32_e64 v69, |v65|, v220
	v_exp_f32_e32 v68, v68
	v_exp_f32_e32 v69, v69
	v_min_f32_e32 v70, 0, v64
	v_min_f32_e32 v71, 0, v65
	v_pk_add_f32 v[68:69], v[68:69], v[222:223]
	s_nop 0
	v_log_f32_e32 v138, v68
	v_log_f32_e32 v139, v69
	s_nop 0
	v_pk_mul_f32 v[140:141], v[138:139], v[224:225]
	s_nop 0
	v_pk_fma_f32 v[142:143], v[138:139], v[224:225], v[140:141] neg_lo:[0,0,1] neg_hi:[0,0,1]
	s_nop 0
	v_pk_fma_f32 v[142:143], v[138:139], v[226:227], v[142:143]
	s_nop 0
	v_pk_fma_f32 v[142:143], v[138:139], v[224:225], v[142:143]
	s_nop 0
	v_pk_add_f32 v[144:145], v[70:71], v[142:143] neg_lo:[0,1] neg_hi:[0,1]
	s_nop 0
	v_pk_mul_f32 v[144:145], v[144:145], v[214:215]
	s_nop 1
	v_add_f32_dpp v144, v144, v144 row_shr:1 row_mask:0xf bank_mask:0xf
	v_add_f32_dpp v145, v145, v145 row_shr:1 row_mask:0xf bank_mask:0xf
	s_nop 0
	v_add_f32_dpp v144, v144, v144 row_shr:2 row_mask:0xf bank_mask:0xf
	v_add_f32_dpp v145, v145, v145 row_shr:2 row_mask:0xf bank_mask:0xf
	s_nop 0
	v_add_f32_dpp v144, v144, v144 row_shr:4 row_mask:0xf bank_mask:0xf
	v_add_f32_dpp v145, v145, v145 row_shr:4 row_mask:0xf bank_mask:0xf
	s_nop 0
	v_add_f32_dpp v144, v144, v144 row_shr:8 row_mask:0xf bank_mask:0xf
	v_add_f32_dpp v145, v145, v145 row_shr:8 row_mask:0xf bank_mask:0xf
	s_nop 0
	v_add_f32_dpp v144, v144, v144 row_bcast:15 row_mask:0xa bank_mask:0xf
	v_add_f32_dpp v145, v145, v145 row_bcast:15 row_mask:0xa bank_mask:0xf
	s_nop 0
	v_add_f32_dpp v144, v144, v144 row_bcast:31 row_mask:0xc bank_mask:0xf
	v_add_f32_dpp v145, v145, v145 row_bcast:31 row_mask:0xc bank_mask:0xf
	s_nop 0
	v_readlane_b32 s98, v144, 63
	v_readlane_b32 s99, v145, 63
	s_nop 1
	v_pk_add_f32 v[146:147], s[98:99], v[144:145] neg_lo:[0,1] neg_hi:[0,1]
	v_mul_f32_e64 v152, s98, v228
	v_mul_f32_e64 v153, s99, v228
	v_pk_mul_f32 v[146:147], v[146:147], v[228:229]
	v_exp_f32_e32 v152, v152
	v_exp_f32_e32 v153, v153
	v_exp_f32_e32 v146, v146
	v_exp_f32_e32 v147, v147
	s_nop 0
	v_pk_mul_f32 v[146:147], v[146:147], v[148:149]
	s_nop 0
	v_cvt_pk_bf16_f32 v150, v146, v147
	s_nop 0
	ds_write_b16 v172, v150 offset:0
	ds_write_b16_d16_hi v172, v150 offset:128
	s_and_saveexec_b64 s[20:21], vcc
	ds_write_b64 v163, v[152:153] offset:4096
	s_mov_b64 exec, s[20:21]
	s_waitcnt lgkmcnt(0)
	s_barrier
; #define MFMA16(a, b, c) __builtin_amdgcn_mfma_f32_16x16x32_bf16((a), (b), (c), 0, 0, 0)
;     ...
;         for (int n = 0; n < 64; ++n) {
;             const int buf = n & 1;
;             f32x4 a4[4]; bf16x8 vfr[2][2];
; #pragma unroll
;             for (int q = 0; q < 4; ++q) a4[q] = a4n[q];
;             const unsigned kraw = krawn;
; #pragma unroll
;             for (int e = 0; e < 2; ++e)
; #pragma unroll
;                 for (int ks = 0; ks < 2; ++ks) vfr[e][ks] = vfrn[e][ks];
;             if (n + 1 < 64) ldchunk(n + 1);
;             float cum[2];
; #pragma unroll
;             for (int e = 0; e < 2; ++e) {
;                 float z = bb[e];
; #pragma unroll
;                 for (int q = 0; q < 4; ++q) { z += a4[q].x * wa[e][4 * q] + a4[q].y * wa[e][4 * q + 1] + a4[q].z * wa[e][4 * q + 2] + a4[q].w * wa[e][4 * q + 3]; }
;                 cum[e] = (fminf(z, 0.f) - __logf(1.f + __expf(-fabsf(z)))) * (1.f / 16.f);
;             }
; #pragma unroll
;             for (int o = 1; o < 64; o <<= 1) {
;                 const float t0 = __shfl_up(cum[0], o), t1 = __shfl_up(cum[1], o);
;                 if (l >= o) { cum[0] += t0; cum[1] += t1; }
;             }
;             const float tot0 = __shfl(cum[0], 63), tot1 = __shfl(cum[1], 63);
;             kdl[(buf * 16 + 2 * w) * 64 + l] = f2bf(bf2f(kraw & 0xffffu) * __expf(tot0 - cum[0]));
;             kdl[(buf * 16 + 2 * w + 1) * 64 + l] = f2bf(bf2f(kraw >> 16) * __expf(tot1 - cum[1]));
;             if (l == 0) { decl[buf * 16 + 2 * w] = __expf(tot0); decl[buf * 16 + 2 * w + 1] = __expf(tot1); }
;             __syncthreads();
;             const f32x4 d4 = *(const f32x4*)(decl + buf * 16 + (l >> 4) * 4);
; #pragma unroll
;             for (int e = 0; e < 2; ++e) acc[e] = acc[e] * d4;
; #pragma unroll
;             for (int ks = 0; ks < 2; ++ks) {
;                 const bf16x8 af = *(const bf16x8*)(kdl + (buf * 16 + (l & 15)) * 64 + ks * 32 + (l >> 4) * 8);
; #pragma unroll
;                 for (int e = 0; e < 2; ++e) acc[e] = MFMA16(af, vfr[e][ks], acc[e]);
;             }
;             const int cidx = b * 64 + n;
; #pragma unroll
;             for (int e = 0; e < 2; ++e) {
;                 const int vv = (2 * w + e) * 16 + (l & 15);
;                 *(u32x2*)(ST + (((size_t)(cidx * 4 + hh)) * 256 + vv) * 128 + ksl * 16 + (l >> 4) * 4) = pk4(acc[e].x, acc[e].y, acc[e].z, acc[e].w);
;             }
	ds_read_b128 v[154:157], v75 offset:0
	ds_read_b128 v[240:243], v164 offset:4096
	ds_read_b128 v[236:239], v75 offset:64
	ds_read_b128 v[8:11], v29 offset:5120
	ds_read_b128 v[12:15], v29 offset:5136
	ds_read_b128 v[16:19], v29 offset:5152
	ds_read_b128 v[20:23], v29 offset:5168
	ds_read_b32 v24, v31 offset:2080
	s_waitcnt lgkmcnt(6)
	v_pk_mul_f32 v[0:1], v[0:1], v[240:241]
	v_pk_mul_f32 v[2:3], v[2:3], v[242:243]
	v_pk_mul_f32 v[4:5], v[4:5], v[240:241]
	v_pk_mul_f32 v[6:7], v[6:7], v[242:243]
	s_waitcnt vmcnt(16)
	s_nop 0
	v_mfma_f32_16x16x32_bf16 v[0:3], v[154:157], v[178:181], v[0:3]
	v_mfma_f32_16x16x32_bf16 v[4:7], v[154:157], v[186:189], v[4:7]
	s_waitcnt lgkmcnt(5)
	v_mfma_f32_16x16x32_bf16 v[0:3], v[236:239], v[182:185], v[0:3]
	v_mfma_f32_16x16x32_bf16 v[4:7], v[236:239], v[190:193], v[4:7]
	s_nop 7
	v_cvt_pk_bf16_f32 v244, v0, v1
	v_cvt_pk_bf16_f32 v245, v2, v3
	v_cvt_pk_bf16_f32 v246, v4, v5
	v_cvt_pk_bf16_f32 v247, v6, v7
	global_store_dwordx2 v234, v[244:245], s[100:101]
	global_store_dwordx2 v235, v[246:247], s[100:101]
	s_add_u32 s100, s100, 0x40000
	s_addc_u32 s101, s101, 0
	global_load_dwordx2 v[56:57], v230, s[26:27]
	global_load_dword v58, v231, s[58:59]
	s_add_u32 s26, s26, 0x1000
	s_addc_u32 s27, s27, 0
	s_add_u32 s58, s58, 0x10000
	s_addc_u32 s59, s59, 0
	global_load_dwordx4 v[178:181], v232, s[34:35]
	global_load_dwordx4 v[182:185], v232, s[34:35] offset:64
	global_load_dwordx4 v[186:189], v233, s[34:35]
	global_load_dwordx4 v[190:193], v233, s[34:35] offset:64
	s_add_u32 s34, s34, 0x80
	s_addc_u32 s35, s35, 0
	s_waitcnt vmcnt(20)
	ds_write_b64 v28, v[48:49] offset:0
	ds_write_b32 v30, v50 offset:0
	s_waitcnt lgkmcnt(2)
	v_pk_fma_f32 v[64:65], v[8:9], v[86:87], v[118:119] op_sel:[0,0,0] op_sel_hi:[0,1,1]
	v_pk_mul_f32 v[66:67], v[16:17], v[102:103] op_sel:[0,0] op_sel_hi:[0,1]
	v_pk_fma_f32 v[64:65], v[8:9], v[88:89], v[64:65] op_sel:[1,0,0] op_sel_hi:[1,1,1]
	v_pk_fma_f32 v[66:67], v[16:17], v[104:105], v[66:67] op_sel:[1,0,0] op_sel_hi:[1,1,1]
	v_pk_fma_f32 v[64:65], v[10:11], v[90:91], v[64:65] op_sel:[0,0,0] op_sel_hi:[0,1,1]
	v_pk_fma_f32 v[66:67], v[18:19], v[106:107], v[66:67] op_sel:[0,0,0] op_sel_hi:[0,1,1]
	v_pk_fma_f32 v[64:65], v[10:11], v[92:93], v[64:65] op_sel:[1,0,0] op_sel_hi:[1,1,1]
	v_pk_fma_f32 v[66:67], v[18:19], v[108:109], v[66:67] op_sel:[1,0,0] op_sel_hi:[1,1,1]
	v_pk_fma_f32 v[64:65], v[12:13], v[94:95], v[64:65] op_sel:[0,0,0] op_sel_hi:[0,1,1]
	v_pk_fma_f32 v[66:67], v[20:21], v[110:111], v[66:67] op_sel:[0,0,0] op_sel_hi:[0,1,1]
	v_pk_fma_f32 v[64:65], v[12:13], v[96:97], v[64:65] op_sel:[1,0,0] op_sel_hi:[1,1,1]
	v_pk_fma_f32 v[66:67], v[20:21], v[112:113], v[66:67] op_sel:[1,0,0] op_sel_hi:[1,1,1]
	v_pk_fma_f32 v[64:65], v[14:15], v[98:99], v[64:65] op_sel:[0,0,0] op_sel_hi:[0,1,1]
	v_pk_fma_f32 v[66:67], v[22:23], v[114:115], v[66:67] op_sel:[0,0,0] op_sel_hi:[0,1,1]
	v_pk_fma_f32 v[64:65], v[14:15], v[100:101], v[64:65] op_sel:[1,0,0] op_sel_hi:[1,1,1]
	v_pk_fma_f32 v[66:67], v[22:23], v[116:117], v[66:67] op_sel:[1,0,0] op_sel_hi:[1,1,1]
	v_lshlrev_b32_e32 v148, 16, v24
	v_pk_add_f32 v[64:65], v[64:65], v[66:67]
	v_and_b32_e32 v149, 0xffff0000, v24
	v_mul_f32_e64 v68, |v64|, v220
	v_mul_f32_e64 v69, |v65|, v220
	v_exp_f32_e32 v68, v68
	v_exp_f32_e32 v69, v69
	v_min_f32_e32 v70, 0, v64
	v_min_f32_e32 v71, 0, v65
	v_pk_add_f32 v[68:69], v[68:69], v[222:223]
	s_nop 0
	v_log_f32_e32 v138, v68
	v_log_f32_e32 v139, v69
	s_nop 0
	v_pk_mul_f32 v[140:141], v[138:139], v[224:225]
	s_nop 0
	v_pk_fma_f32 v[142:143], v[138:139], v[224:225], v[140:141] neg_lo:[0,0,1] neg_hi:[0,0,1]
	s_nop 0
	v_pk_fma_f32 v[142:143], v[138:139], v[226:227], v[142:143]
	s_nop 0
	v_pk_fma_f32 v[142:143], v[138:139], v[224:225], v[142:143]
	s_nop 0
	v_pk_add_f32 v[144:145], v[70:71], v[142:143] neg_lo:[0,1] neg_hi:[0,1]
	s_nop 0
	v_pk_mul_f32 v[144:145], v[144:145], v[214:215]
	s_nop 1
	v_add_f32_dpp v144, v144, v144 row_shr:1 row_mask:0xf bank_mask:0xf
	v_add_f32_dpp v145, v145, v145 row_shr:1 row_mask:0xf bank_mask:0xf
	s_nop 0
	v_add_f32_dpp v144, v144, v144 row_shr:2 row_mask:0xf bank_mask:0xf
	v_add_f32_dpp v145, v145, v145 row_shr:2 row_mask:0xf bank_mask:0xf
	s_nop 0
	v_add_f32_dpp v144, v144, v144 row_shr:4 row_mask:0xf bank_mask:0xf
	v_add_f32_dpp v145, v145, v145 row_shr:4 row_mask:0xf bank_mask:0xf
	s_nop 0
	v_add_f32_dpp v144, v144, v144 row_shr:8 row_mask:0xf bank_mask:0xf
	v_add_f32_dpp v145, v145, v145 row_shr:8 row_mask:0xf bank_mask:0xf
	s_nop 0
	v_add_f32_dpp v144, v144, v144 row_bcast:15 row_mask:0xa bank_mask:0xf
	v_add_f32_dpp v145, v145, v145 row_bcast:15 row_mask:0xa bank_mask:0xf
	s_nop 0
	v_add_f32_dpp v144, v144, v144 row_bcast:31 row_mask:0xc bank_mask:0xf
	v_add_f32_dpp v145, v145, v145 row_bcast:31 row_mask:0xc bank_mask:0xf
	s_nop 0
	v_readlane_b32 s98, v144, 63
	v_readlane_b32 s99, v145, 63
	s_nop 1
	v_pk_add_f32 v[146:147], s[98:99], v[144:145] neg_lo:[0,1] neg_hi:[0,1]
	v_mul_f32_e64 v152, s98, v228
	v_mul_f32_e64 v153, s99, v228
	v_pk_mul_f32 v[146:147], v[146:147], v[228:229]
	v_exp_f32_e32 v152, v152
	v_exp_f32_e32 v153, v153
	v_exp_f32_e32 v146, v146
	v_exp_f32_e32 v147, v147
	s_nop 0
	v_pk_mul_f32 v[146:147], v[146:147], v[148:149]
	s_nop 0
	v_cvt_pk_bf16_f32 v150, v146, v147
	s_nop 0
	ds_write_b16 v172, v150 offset:2048
	ds_write_b16_d16_hi v172, v150 offset:2176
	s_and_saveexec_b64 s[20:21], vcc
	ds_write_b64 v163, v[152:153] offset:4160
	s_mov_b64 exec, s[20:21]
	s_waitcnt lgkmcnt(0)
	s_barrier
; #define MFMA16(a, b, c) __builtin_amdgcn_mfma_f32_16x16x32_bf16((a), (b), (c), 0, 0, 0)
;     ...
;         for (int n = 0; n < 64; ++n) {
;             const int buf = n & 1;
;             f32x4 a4[4]; bf16x8 vfr[2][2];
; #pragma unroll
;             for (int q = 0; q < 4; ++q) a4[q] = a4n[q];
;             const unsigned kraw = krawn;
; #pragma unroll
;             for (int e = 0; e < 2; ++e)
; #pragma unroll
;                 for (int ks = 0; ks < 2; ++ks) vfr[e][ks] = vfrn[e][ks];
;             if (n + 1 < 64) ldchunk(n + 1);
;             float cum[2];
; #pragma unroll
;             for (int e = 0; e < 2; ++e) {
;                 float z = bb[e];
; #pragma unroll
;                 for (int q = 0; q < 4; ++q) { z += a4[q].x * wa[e][4 * q] + a4[q].y * wa[e][4 * q + 1] + a4[q].z * wa[e][4 * q + 2] + a4[q].w * wa[e][4 * q + 3]; }
;                 cum[e] = (fminf(z, 0.f) - __logf(1.f + __expf(-fabsf(z)))) * (1.f / 16.f);
;             }
; #pragma unroll
;             for (int o = 1; o < 64; o <<= 1) {
;                 const float t0 = __shfl_up(cum[0], o), t1 = __shfl_up(cum[1], o);
;                 if (l >= o) { cum[0] += t0; cum[1] += t1; }
;             }
;             const float tot0 = __shfl(cum[0], 63), tot1 = __shfl(cum[1], 63);
;             kdl[(buf * 16 + 2 * w) * 64 + l] = f2bf(bf2f(kraw & 0xffffu) * __expf(tot0 - cum[0]));
;             kdl[(buf * 16 + 2 * w + 1) * 64 + l] = f2bf(bf2f(kraw >> 16) * __expf(tot1 - cum[1]));
;             if (l == 0) { decl[buf * 16 + 2 * w] = __expf(tot0); decl[buf * 16 + 2 * w + 1] = __expf(tot1); }
;             __syncthreads();
;             const f32x4 d4 = *(const f32x4*)(decl + buf * 16 + (l >> 4) * 4);
; #pragma unroll
;             for (int e = 0; e < 2; ++e) acc[e] = acc[e] * d4;
; #pragma unroll
;             for (int ks = 0; ks < 2; ++ks) {
;                 const bf16x8 af = *(const bf16x8*)(kdl + (buf * 16 + (l & 15)) * 64 + ks * 32 + (l >> 4) * 8);
; #pragma unroll
;                 for (int e = 0; e < 2; ++e) acc[e] = MFMA16(af, vfr[e][ks], acc[e]);
;             }
;             const int cidx = b * 64 + n;
; #pragma unroll
;             for (int e = 0; e < 2; ++e) {
;                 const int vv = (2 * w + e) * 16 + (l & 15);
;                 *(u32x2*)(ST + (((size_t)(cidx * 4 + hh)) * 256 + vv) * 128 + ksl * 16 + (l >> 4) * 4) = pk4(acc[e].x, acc[e].y, acc[e].z, acc[e].w);
;             }
	ds_read_b128 v[154:157], v75 offset:2048
	ds_read_b128 v[240:243], v164 offset:4160
	ds_read_b128 v[236:239], v75 offset:2112
	ds_read_b128 v[8:11], v29 offset:0
	ds_read_b128 v[12:15], v29 offset:16
	ds_read_b128 v[16:19], v29 offset:32
	ds_read_b128 v[20:23], v29 offset:48
	ds_read_b32 v24, v31 offset:0
	s_waitcnt lgkmcnt(6)
	v_pk_mul_f32 v[0:1], v[0:1], v[240:241]
	v_pk_mul_f32 v[2:3], v[2:3], v[242:243]
	v_pk_mul_f32 v[4:5], v[4:5], v[240:241]
	v_pk_mul_f32 v[6:7], v[6:7], v[242:243]
	s_waitcnt vmcnt(16)
	s_nop 0
	v_mfma_f32_16x16x32_bf16 v[0:3], v[154:157], v[194:197], v[0:3]
	v_mfma_f32_16x16x32_bf16 v[4:7], v[154:157], v[202:205], v[4:7]
	s_waitcnt lgkmcnt(5)
	v_mfma_f32_16x16x32_bf16 v[0:3], v[236:239], v[198:201], v[0:3]
	v_mfma_f32_16x16x32_bf16 v[4:7], v[236:239], v[206:209], v[4:7]
	s_nop 7
	v_cvt_pk_bf16_f32 v244, v0, v1
	v_cvt_pk_bf16_f32 v245, v2, v3
	v_cvt_pk_bf16_f32 v246, v4, v5
	v_cvt_pk_bf16_f32 v247, v6, v7
	global_store_dwordx2 v234, v[244:245], s[100:101]
	global_store_dwordx2 v235, v[246:247], s[100:101]
	s_add_u32 s100, s100, 0x40000
	s_addc_u32 s101, s101, 0
	s_sub_u32 s28, s28, 1
	s_cmp_lg_u32 s28, 0
	s_cbranch_scc1 .Lgscan_loop
	global_load_dwordx2 v[48:49], v230, s[26:27]
	global_load_dword v50, v231, s[58:59]
	s_add_u32 s26, s26, 0x1000
	s_addc_u32 s27, s27, 0
	s_add_u32 s58, s58, 0x10000
	s_addc_u32 s59, s59, 0
	global_load_dwordx4 v[194:197], v232, s[34:35]
	global_load_dwordx4 v[198:201], v232, s[34:35] offset:64
	global_load_dwordx4 v[202:205], v233, s[34:35]
	global_load_dwordx4 v[206:209], v233, s[34:35] offset:64
	s_add_u32 s34, s34, 0x80
	s_addc_u32 s35, s35, 0
	s_waitcnt vmcnt(20)
	ds_write_b64 v28, v[52:53] offset:5120
	ds_write_b32 v30, v54 offset:2080
	s_waitcnt lgkmcnt(2)
	v_pk_fma_f32 v[64:65], v[8:9], v[86:87], v[118:119] op_sel:[0,0,0] op_sel_hi:[0,1,1]
	v_pk_mul_f32 v[66:67], v[16:17], v[102:103] op_sel:[0,0] op_sel_hi:[0,1]
	v_pk_fma_f32 v[64:65], v[8:9], v[88:89], v[64:65] op_sel:[1,0,0] op_sel_hi:[1,1,1]
	v_pk_fma_f32 v[66:67], v[16:17], v[104:105], v[66:67] op_sel:[1,0,0] op_sel_hi:[1,1,1]
	v_pk_fma_f32 v[64:65], v[10:11], v[90:91], v[64:65] op_sel:[0,0,0] op_sel_hi:[0,1,1]
	v_pk_fma_f32 v[66:67], v[18:19], v[106:107], v[66:67] op_sel:[0,0,0] op_sel_hi:[0,1,1]
	v_pk_fma_f32 v[64:65], v[10:11], v[92:93], v[64:65] op_sel:[1,0,0] op_sel_hi:[1,1,1]
	v_pk_fma_f32 v[66:67], v[18:19], v[108:109], v[66:67] op_sel:[1,0,0] op_sel_hi:[1,1,1]
	v_pk_fma_f32 v[64:65], v[12:13], v[94:95], v[64:65] op_sel:[0,0,0] op_sel_hi:[0,1,1]
	v_pk_fma_f32 v[66:67], v[20:21], v[110:111], v[66:67] op_sel:[0,0,0] op_sel_hi:[0,1,1]
	v_pk_fma_f32 v[64:65], v[12:13], v[96:97], v[64:65] op_sel:[1,0,0] op_sel_hi:[1,1,1]
	v_pk_fma_f32 v[66:67], v[20:21], v[112:113], v[66:67] op_sel:[1,0,0] op_sel_hi:[1,1,1]
	v_pk_fma_f32 v[64:65], v[14:15], v[98:99], v[64:65] op_sel:[0,0,0] op_sel_hi:[0,1,1]
	v_pk_fma_f32 v[66:67], v[22:23], v[114:115], v[66:67] op_sel:[0,0,0] op_sel_hi:[0,1,1]
	v_pk_fma_f32 v[64:65], v[14:15], v[100:101], v[64:65] op_sel:[1,0,0] op_sel_hi:[1,1,1]
	v_pk_fma_f32 v[66:67], v[22:23], v[116:117], v[66:67] op_sel:[1,0,0] op_sel_hi:[1,1,1]
	v_lshlrev_b32_e32 v148, 16, v24
	v_pk_add_f32 v[64:65], v[64:65], v[66:67]
	v_and_b32_e32 v149, 0xffff0000, v24
	v_mul_f32_e64 v68, |v64|, v220
	v_mul_f32_e64 v69, |v65|, v220
	v_exp_f32_e32 v68, v68
	v_exp_f32_e32 v69, v69
	v_min_f32_e32 v70, 0, v64
	v_min_f32_e32 v71, 0, v65
	v_pk_add_f32 v[68:69], v[68:69], v[222:223]
	s_nop 0
	v_log_f32_e32 v138, v68
	v_log_f32_e32 v139, v69
	s_nop 0
	v_pk_mul_f32 v[140:141], v[138:139], v[224:225]
	s_nop 0
	v_pk_fma_f32 v[142:143], v[138:139], v[224:225], v[140:141] neg_lo:[0,0,1] neg_hi:[0,0,1]
	s_nop 0
	v_pk_fma_f32 v[142:143], v[138:139], v[226:227], v[142:143]
	s_nop 0
	v_pk_fma_f32 v[142:143], v[138:139], v[224:225], v[142:143]
	s_nop 0
	v_pk_add_f32 v[144:145], v[70:71], v[142:143] neg_lo:[0,1] neg_hi:[0,1]
	s_nop 0
	v_pk_mul_f32 v[144:145], v[144:145], v[214:215]
	s_nop 1
	v_add_f32_dpp v144, v144, v144 row_shr:1 row_mask:0xf bank_mask:0xf
	v_add_f32_dpp v145, v145, v145 row_shr:1 row_mask:0xf bank_mask:0xf
	s_nop 0
	v_add_f32_dpp v144, v144, v144 row_shr:2 row_mask:0xf bank_mask:0xf
	v_add_f32_dpp v145, v145, v145 row_shr:2 row_mask:0xf bank_mask:0xf
	s_nop 0
	v_add_f32_dpp v144, v144, v144 row_shr:4 row_mask:0xf bank_mask:0xf
	v_add_f32_dpp v145, v145, v145 row_shr:4 row_mask:0xf bank_mask:0xf
	s_nop 0
	v_add_f32_dpp v144, v144, v144 row_shr:8 row_mask:0xf bank_mask:0xf
	v_add_f32_dpp v145, v145, v145 row_shr:8 row_mask:0xf bank_mask:0xf
	s_nop 0
	v_add_f32_dpp v144, v144, v144 row_bcast:15 row_mask:0xa bank_mask:0xf
	v_add_f32_dpp v145, v145, v145 row_bcast:15 row_mask:0xa bank_mask:0xf
	s_nop 0
	v_add_f32_dpp v144, v144, v144 row_bcast:31 row_mask:0xc bank_mask:0xf
	v_add_f32_dpp v145, v145, v145 row_bcast:31 row_mask:0xc bank_mask:0xf
	s_nop 0
	v_readlane_b32 s98, v144, 63
	v_readlane_b32 s99, v145, 63
	s_nop 1
	v_pk_add_f32 v[146:147], s[98:99], v[144:145] neg_lo:[0,1] neg_hi:[0,1]
	v_mul_f32_e64 v152, s98, v228
	v_mul_f32_e64 v153, s99, v228
	v_pk_mul_f32 v[146:147], v[146:147], v[228:229]
	v_exp_f32_e32 v152, v152
	v_exp_f32_e32 v153, v153
	v_exp_f32_e32 v146, v146
	v_exp_f32_e32 v147, v147
	s_nop 0
	v_pk_mul_f32 v[146:147], v[146:147], v[148:149]
	s_nop 0
	v_cvt_pk_bf16_f32 v150, v146, v147
	s_nop 0
	ds_write_b16 v172, v150 offset:0
	ds_write_b16_d16_hi v172, v150 offset:128
	s_and_saveexec_b64 s[20:21], vcc
	ds_write_b64 v163, v[152:153] offset:4096
	s_mov_b64 exec, s[20:21]
	s_waitcnt lgkmcnt(0)
	s_barrier
; #define MFMA16(a, b, c) __builtin_amdgcn_mfma_f32_16x16x32_bf16((a), (b), (c), 0, 0, 0)
;     ...
;         for (int n = 0; n < 64; ++n) {
;             const int buf = n & 1;
;             f32x4 a4[4]; bf16x8 vfr[2][2];
; #pragma unroll
;             for (int q = 0; q < 4; ++q) a4[q] = a4n[q];
;             const unsigned kraw = krawn;
; #pragma unroll
;             for (int e = 0; e < 2; ++e)
; #pragma unroll
;                 for (int ks = 0; ks < 2; ++ks) vfr[e][ks] = vfrn[e][ks];
;             if (n + 1 < 64) ldchunk(n + 1);
;             float cum[2];
; #pragma unroll
;             for (int e = 0; e < 2; ++e) {
;                 float z = bb[e];
; #pragma unroll
;                 for (int q = 0; q < 4; ++q) { z += a4[q].x * wa[e][4 * q] + a4[q].y * wa[e][4 * q + 1] + a4[q].z * wa[e][4 * q + 2] + a4[q].w * wa[e][4 * q + 3]; }
;                 cum[e] = (fminf(z, 0.f) - __logf(1.f + __expf(-fabsf(z)))) * (1.f / 16.f);
;             }
; #pragma unroll
;             for (int o = 1; o < 64; o <<= 1) {
;                 const float t0 = __shfl_up(cum[0], o), t1 = __shfl_up(cum[1], o);
;                 if (l >= o) { cum[0] += t0; cum[1] += t1; }
;             }
;             const float tot0 = __shfl(cum[0], 63), tot1 = __shfl(cum[1], 63);
;             kdl[(buf * 16 + 2 * w) * 64 + l] = f2bf(bf2f(kraw & 0xffffu) * __expf(tot0 - cum[0]));
;             kdl[(buf * 16 + 2 * w + 1) * 64 + l] = f2bf(bf2f(kraw >> 16) * __expf(tot1 - cum[1]));
;             if (l == 0) { decl[buf * 16 + 2 * w] = __expf(tot0); decl[buf * 16 + 2 * w + 1] = __expf(tot1); }
;             __syncthreads();
;             const f32x4 d4 = *(const f32x4*)(decl + buf * 16 + (l >> 4) * 4);
; #pragma unroll
;             for (int e = 0; e < 2; ++e) acc[e] = acc[e] * d4;
; #pragma unroll
;             for (int ks = 0; ks < 2; ++ks) {
;                 const bf16x8 af = *(const bf16x8*)(kdl + (buf * 16 + (l & 15)) * 64 + ks * 32 + (l >> 4) * 8);
; #pragma unroll
;                 for (int e = 0; e < 2; ++e) acc[e] = MFMA16(af, vfr[e][ks], acc[e]);
;             }
;             const int cidx = b * 64 + n;
; #pragma unroll
;             for (int e = 0; e < 2; ++e) {
;                 const int vv = (2 * w + e) * 16 + (l & 15);
;                 *(u32x2*)(ST + (((size_t)(cidx * 4 + hh)) * 256 + vv) * 128 + ksl * 16 + (l >> 4) * 4) = pk4(acc[e].x, acc[e].y, acc[e].z, acc[e].w);
;             }
	ds_read_b128 v[154:157], v75 offset:0
	ds_read_b128 v[240:243], v164 offset:4096
	ds_read_b128 v[236:239], v75 offset:64
	ds_read_b128 v[8:11], v29 offset:5120
	ds_read_b128 v[12:15], v29 offset:5136
	ds_read_b128 v[16:19], v29 offset:5152
	ds_read_b128 v[20:23], v29 offset:5168
	ds_read_b32 v24, v31 offset:2080
	s_waitcnt lgkmcnt(6)
	v_pk_mul_f32 v[0:1], v[0:1], v[240:241]
	v_pk_mul_f32 v[2:3], v[2:3], v[242:243]
	v_pk_mul_f32 v[4:5], v[4:5], v[240:241]
	v_pk_mul_f32 v[6:7], v[6:7], v[242:243]
	s_waitcnt vmcnt(16)
	s_nop 0
	v_mfma_f32_16x16x32_bf16 v[0:3], v[154:157], v[32:35], v[0:3]
	v_mfma_f32_16x16x32_bf16 v[4:7], v[154:157], v[40:43], v[4:7]
	s_waitcnt lgkmcnt(5)
	v_mfma_f32_16x16x32_bf16 v[0:3], v[236:239], v[36:39], v[0:3]
	v_mfma_f32_16x16x32_bf16 v[4:7], v[236:239], v[44:47], v[4:7]
	s_nop 7
	v_cvt_pk_bf16_f32 v244, v0, v1
	v_cvt_pk_bf16_f32 v245, v2, v3
	v_cvt_pk_bf16_f32 v246, v4, v5
	v_cvt_pk_bf16_f32 v247, v6, v7
	global_store_dwordx2 v234, v[244:245], s[100:101]
	global_store_dwordx2 v235, v[246:247], s[100:101]
	s_add_u32 s100, s100, 0x40000
	s_addc_u32 s101, s101, 0
	global_load_dwordx4 v[32:35], v232, s[34:35]
	global_load_dwordx4 v[36:39], v232, s[34:35] offset:64
	global_load_dwordx4 v[40:43], v233, s[34:35]
	global_load_dwordx4 v[44:47], v233, s[34:35] offset:64
	s_add_u32 s34, s34, 0x80
	s_addc_u32 s35, s35, 0
	s_waitcnt vmcnt(18)
	ds_write_b64 v28, v[56:57] offset:0
	ds_write_b32 v30, v58 offset:0
	s_waitcnt lgkmcnt(2)
	v_pk_fma_f32 v[64:65], v[8:9], v[86:87], v[118:119] op_sel:[0,0,0] op_sel_hi:[0,1,1]
	v_pk_mul_f32 v[66:67], v[16:17], v[102:103] op_sel:[0,0] op_sel_hi:[0,1]
	v_pk_fma_f32 v[64:65], v[8:9], v[88:89], v[64:65] op_sel:[1,0,0] op_sel_hi:[1,1,1]
	v_pk_fma_f32 v[66:67], v[16:17], v[104:105], v[66:67] op_sel:[1,0,0] op_sel_hi:[1,1,1]
	v_pk_fma_f32 v[64:65], v[10:11], v[90:91], v[64:65] op_sel:[0,0,0] op_sel_hi:[0,1,1]
	v_pk_fma_f32 v[66:67], v[18:19], v[106:107], v[66:67] op_sel:[0,0,0] op_sel_hi:[0,1,1]
	v_pk_fma_f32 v[64:65], v[10:11], v[92:93], v[64:65] op_sel:[1,0,0] op_sel_hi:[1,1,1]
	v_pk_fma_f32 v[66:67], v[18:19], v[108:109], v[66:67] op_sel:[1,0,0] op_sel_hi:[1,1,1]
	v_pk_fma_f32 v[64:65], v[12:13], v[94:95], v[64:65] op_sel:[0,0,0] op_sel_hi:[0,1,1]
	v_pk_fma_f32 v[66:67], v[20:21], v[110:111], v[66:67] op_sel:[0,0,0] op_sel_hi:[0,1,1]
	v_pk_fma_f32 v[64:65], v[12:13], v[96:97], v[64:65] op_sel:[1,0,0] op_sel_hi:[1,1,1]
	v_pk_fma_f32 v[66:67], v[20:21], v[112:113], v[66:67] op_sel:[1,0,0] op_sel_hi:[1,1,1]
	v_pk_fma_f32 v[64:65], v[14:15], v[98:99], v[64:65] op_sel:[0,0,0] op_sel_hi:[0,1,1]
	v_pk_fma_f32 v[66:67], v[22:23], v[114:115], v[66:67] op_sel:[0,0,0] op_sel_hi:[0,1,1]
	v_pk_fma_f32 v[64:65], v[14:15], v[100:101], v[64:65] op_sel:[1,0,0] op_sel_hi:[1,1,1]
	v_pk_fma_f32 v[66:67], v[22:23], v[116:117], v[66:67] op_sel:[1,0,0] op_sel_hi:[1,1,1]
	v_lshlrev_b32_e32 v148, 16, v24
	v_pk_add_f32 v[64:65], v[64:65], v[66:67]
	v_and_b32_e32 v149, 0xffff0000, v24
	v_mul_f32_e64 v68, |v64|, v220
	v_mul_f32_e64 v69, |v65|, v220
	v_exp_f32_e32 v68, v68
	v_exp_f32_e32 v69, v69
	v_min_f32_e32 v70, 0, v64
	v_min_f32_e32 v71, 0, v65
	v_pk_add_f32 v[68:69], v[68:69], v[222:223]
	s_nop 0
	v_log_f32_e32 v138, v68
	v_log_f32_e32 v139, v69
	s_nop 0
	v_pk_mul_f32 v[140:141], v[138:139], v[224:225]
	s_nop 0
	v_pk_fma_f32 v[142:143], v[138:139], v[224:225], v[140:141] neg_lo:[0,0,1] neg_hi:[0,0,1]
	s_nop 0
	v_pk_fma_f32 v[142:143], v[138:139], v[226:227], v[142:143]
	s_nop 0
	v_pk_fma_f32 v[142:143], v[138:139], v[224:225], v[142:143]
	s_nop 0
	v_pk_add_f32 v[144:145], v[70:71], v[142:143] neg_lo:[0,1] neg_hi:[0,1]
	s_nop 0
	v_pk_mul_f32 v[144:145], v[144:145], v[214:215]
	s_nop 1
	v_add_f32_dpp v144, v144, v144 row_shr:1 row_mask:0xf bank_mask:0xf
	v_add_f32_dpp v145, v145, v145 row_shr:1 row_mask:0xf bank_mask:0xf
	s_nop 0
	v_add_f32_dpp v144, v144, v144 row_shr:2 row_mask:0xf bank_mask:0xf
	v_add_f32_dpp v145, v145, v145 row_shr:2 row_mask:0xf bank_mask:0xf
	s_nop 0
	v_add_f32_dpp v144, v144, v144 row_shr:4 row_mask:0xf bank_mask:0xf
	v_add_f32_dpp v145, v145, v145 row_shr:4 row_mask:0xf bank_mask:0xf
	s_nop 0
	v_add_f32_dpp v144, v144, v144 row_shr:8 row_mask:0xf bank_mask:0xf
	v_add_f32_dpp v145, v145, v145 row_shr:8 row_mask:0xf bank_mask:0xf
	s_nop 0
	v_add_f32_dpp v144, v144, v144 row_bcast:15 row_mask:0xa bank_mask:0xf
	v_add_f32_dpp v145, v145, v145 row_bcast:15 row_mask:0xa bank_mask:0xf
	s_nop 0
	v_add_f32_dpp v144, v144, v144 row_bcast:31 row_mask:0xc bank_mask:0xf
	v_add_f32_dpp v145, v145, v145 row_bcast:31 row_mask:0xc bank_mask:0xf
	s_nop 0
	v_readlane_b32 s98, v144, 63
	v_readlane_b32 s99, v145, 63
	s_nop 1
	v_pk_add_f32 v[146:147], s[98:99], v[144:145] neg_lo:[0,1] neg_hi:[0,1]
	v_mul_f32_e64 v152, s98, v228
	v_mul_f32_e64 v153, s99, v228
	v_pk_mul_f32 v[146:147], v[146:147], v[228:229]
	v_exp_f32_e32 v152, v152
	v_exp_f32_e32 v153, v153
	v_exp_f32_e32 v146, v146
	v_exp_f32_e32 v147, v147
	s_nop 0
	v_pk_mul_f32 v[146:147], v[146:147], v[148:149]
	s_nop 0
	v_cvt_pk_bf16_f32 v150, v146, v147
	s_nop 0
	ds_write_b16 v172, v150 offset:2048
	ds_write_b16_d16_hi v172, v150 offset:2176
	s_and_saveexec_b64 s[20:21], vcc
	ds_write_b64 v163, v[152:153] offset:4160
	s_mov_b64 exec, s[20:21]
	s_waitcnt lgkmcnt(0)
	s_barrier
; #define MFMA16(a, b, c) __builtin_amdgcn_mfma_f32_16x16x32_bf16((a), (b), (c), 0, 0, 0)
;     ...
;         for (int n = 0; n < 64; ++n) {
;             const int buf = n & 1;
;             f32x4 a4[4]; bf16x8 vfr[2][2];
; #pragma unroll
;             for (int q = 0; q < 4; ++q) a4[q] = a4n[q];
;             const unsigned kraw = krawn;
; #pragma unroll
;             for (int e = 0; e < 2; ++e)
; #pragma unroll
;                 for (int ks = 0; ks < 2; ++ks) vfr[e][ks] = vfrn[e][ks];
;             if (n + 1 < 64) ldchunk(n + 1);
;             float cum[2];
; #pragma unroll
;             for (int e = 0; e < 2; ++e) {
;                 float z = bb[e];
; #pragma unroll
;                 for (int q = 0; q < 4; ++q) { z += a4[q].x * wa[e][4 * q] + a4[q].y * wa[e][4 * q + 1] + a4[q].z * wa[e][4 * q + 2] + a4[q].w * wa[e][4 * q + 3]; }
;                 cum[e] = (fminf(z, 0.f) - __logf(1.f + __expf(-fabsf(z)))) * (1.f / 16.f);
;             }
; #pragma unroll
;             for (int o = 1; o < 64; o <<= 1) {
;                 const float t0 = __shfl_up(cum[0], o), t1 = __shfl_up(cum[1], o);
;                 if (l >= o) { cum[0] += t0; cum[1] += t1; }
;             }
;             const float tot0 = __shfl(cum[0], 63), tot1 = __shfl(cum[1], 63);
;             kdl[(buf * 16 + 2 * w) * 64 + l] = f2bf(bf2f(kraw & 0xffffu) * __expf(tot0 - cum[0]));
;             kdl[(buf * 16 + 2 * w + 1) * 64 + l] = f2bf(bf2f(kraw >> 16) * __expf(tot1 - cum[1]));
;             if (l == 0) { decl[buf * 16 + 2 * w] = __expf(tot0); decl[buf * 16 + 2 * w + 1] = __expf(tot1); }
;             __syncthreads();
;             const f32x4 d4 = *(const f32x4*)(decl + buf * 16 + (l >> 4) * 4);
; #pragma unroll
;             for (int e = 0; e < 2; ++e) acc[e] = acc[e] * d4;
; #pragma unroll
;             for (int ks = 0; ks < 2; ++ks) {
;                 const bf16x8 af = *(const bf16x8*)(kdl + (buf * 16 + (l & 15)) * 64 + ks * 32 + (l >> 4) * 8);
; #pragma unroll
;                 for (int e = 0; e < 2; ++e) acc[e] = MFMA16(af, vfr[e][ks], acc[e]);
;             }
;             const int cidx = b * 64 + n;
; #pragma unroll
;             for (int e = 0; e < 2; ++e) {
;                 const int vv = (2 * w + e) * 16 + (l & 15);
;                 *(u32x2*)(ST + (((size_t)(cidx * 4 + hh)) * 256 + vv) * 128 + ksl * 16 + (l >> 4) * 4) = pk4(acc[e].x, acc[e].y, acc[e].z, acc[e].w);
;             }
	ds_read_b128 v[154:157], v75 offset:2048
	ds_read_b128 v[240:243], v164 offset:4160
	ds_read_b128 v[236:239], v75 offset:2112
	ds_read_b128 v[8:11], v29 offset:0
	ds_read_b128 v[12:15], v29 offset:16
	ds_read_b128 v[16:19], v29 offset:32
	ds_read_b128 v[20:23], v29 offset:48
	ds_read_b32 v24, v31 offset:0
	s_waitcnt lgkmcnt(6)
	v_pk_mul_f32 v[0:1], v[0:1], v[240:241]
	v_pk_mul_f32 v[2:3], v[2:3], v[242:243]
	v_pk_mul_f32 v[4:5], v[4:5], v[240:241]
	v_pk_mul_f32 v[6:7], v[6:7], v[242:243]
	s_waitcnt vmcnt(14)
	s_nop 0
	v_mfma_f32_16x16x32_bf16 v[0:3], v[154:157], v[178:181], v[0:3]
	v_mfma_f32_16x16x32_bf16 v[4:7], v[154:157], v[186:189], v[4:7]
	s_waitcnt lgkmcnt(5)
	v_mfma_f32_16x16x32_bf16 v[0:3], v[236:239], v[182:185], v[0:3]
	v_mfma_f32_16x16x32_bf16 v[4:7], v[236:239], v[190:193], v[4:7]
	s_nop 7
	v_cvt_pk_bf16_f32 v244, v0, v1
	v_cvt_pk_bf16_f32 v245, v2, v3
	v_cvt_pk_bf16_f32 v246, v4, v5
	v_cvt_pk_bf16_f32 v247, v6, v7
	global_store_dwordx2 v234, v[244:245], s[100:101]
	global_store_dwordx2 v235, v[246:247], s[100:101]
	s_add_u32 s100, s100, 0x40000
	s_addc_u32 s101, s101, 0
	s_waitcnt vmcnt(12)
	ds_write_b64 v28, v[48:49] offset:5120
	ds_write_b32 v30, v50 offset:2080
	s_waitcnt lgkmcnt(2)
	v_pk_fma_f32 v[64:65], v[8:9], v[86:87], v[118:119] op_sel:[0,0,0] op_sel_hi:[0,1,1]
	v_pk_mul_f32 v[66:67], v[16:17], v[102:103] op_sel:[0,0] op_sel_hi:[0,1]
	v_pk_fma_f32 v[64:65], v[8:9], v[88:89], v[64:65] op_sel:[1,0,0] op_sel_hi:[1,1,1]
	v_pk_fma_f32 v[66:67], v[16:17], v[104:105], v[66:67] op_sel:[1,0,0] op_sel_hi:[1,1,1]
	v_pk_fma_f32 v[64:65], v[10:11], v[90:91], v[64:65] op_sel:[0,0,0] op_sel_hi:[0,1,1]
	v_pk_fma_f32 v[66:67], v[18:19], v[106:107], v[66:67] op_sel:[0,0,0] op_sel_hi:[0,1,1]
	v_pk_fma_f32 v[64:65], v[10:11], v[92:93], v[64:65] op_sel:[1,0,0] op_sel_hi:[1,1,1]
	v_pk_fma_f32 v[66:67], v[18:19], v[108:109], v[66:67] op_sel:[1,0,0] op_sel_hi:[1,1,1]
	v_pk_fma_f32 v[64:65], v[12:13], v[94:95], v[64:65] op_sel:[0,0,0] op_sel_hi:[0,1,1]
	v_pk_fma_f32 v[66:67], v[20:21], v[110:111], v[66:67] op_sel:[0,0,0] op_sel_hi:[0,1,1]
	v_pk_fma_f32 v[64:65], v[12:13], v[96:97], v[64:65] op_sel:[1,0,0] op_sel_hi:[1,1,1]
	v_pk_fma_f32 v[66:67], v[20:21], v[112:113], v[66:67] op_sel:[1,0,0] op_sel_hi:[1,1,1]
	v_pk_fma_f32 v[64:65], v[14:15], v[98:99], v[64:65] op_sel:[0,0,0] op_sel_hi:[0,1,1]
	v_pk_fma_f32 v[66:67], v[22:23], v[114:115], v[66:67] op_sel:[0,0,0] op_sel_hi:[0,1,1]
	v_pk_fma_f32 v[64:65], v[14:15], v[100:101], v[64:65] op_sel:[1,0,0] op_sel_hi:[1,1,1]
	v_pk_fma_f32 v[66:67], v[22:23], v[116:117], v[66:67] op_sel:[1,0,0] op_sel_hi:[1,1,1]
	v_lshlrev_b32_e32 v148, 16, v24
	v_pk_add_f32 v[64:65], v[64:65], v[66:67]
	v_and_b32_e32 v149, 0xffff0000, v24
	v_mul_f32_e64 v68, |v64|, v220
	v_mul_f32_e64 v69, |v65|, v220
	v_exp_f32_e32 v68, v68
	v_exp_f32_e32 v69, v69
	v_min_f32_e32 v70, 0, v64
	v_min_f32_e32 v71, 0, v65
	v_pk_add_f32 v[68:69], v[68:69], v[222:223]
	s_nop 0
	v_log_f32_e32 v138, v68
	v_log_f32_e32 v139, v69
	s_nop 0
	v_pk_mul_f32 v[140:141], v[138:139], v[224:225]
	s_nop 0
	v_pk_fma_f32 v[142:143], v[138:139], v[224:225], v[140:141] neg_lo:[0,0,1] neg_hi:[0,0,1]
	s_nop 0
	v_pk_fma_f32 v[142:143], v[138:139], v[226:227], v[142:143]
	s_nop 0
	v_pk_fma_f32 v[142:143], v[138:139], v[224:225], v[142:143]
	s_nop 0
	v_pk_add_f32 v[144:145], v[70:71], v[142:143] neg_lo:[0,1] neg_hi:[0,1]
	s_nop 0
	v_pk_mul_f32 v[144:145], v[144:145], v[214:215]
	s_nop 1
	v_add_f32_dpp v144, v144, v144 row_shr:1 row_mask:0xf bank_mask:0xf
	v_add_f32_dpp v145, v145, v145 row_shr:1 row_mask:0xf bank_mask:0xf
	s_nop 0
	v_add_f32_dpp v144, v144, v144 row_shr:2 row_mask:0xf bank_mask:0xf
	v_add_f32_dpp v145, v145, v145 row_shr:2 row_mask:0xf bank_mask:0xf
	s_nop 0
	v_add_f32_dpp v144, v144, v144 row_shr:4 row_mask:0xf bank_mask:0xf
	v_add_f32_dpp v145, v145, v145 row_shr:4 row_mask:0xf bank_mask:0xf
	s_nop 0
	v_add_f32_dpp v144, v144, v144 row_shr:8 row_mask:0xf bank_mask:0xf
	v_add_f32_dpp v145, v145, v145 row_shr:8 row_mask:0xf bank_mask:0xf
	s_nop 0
	v_add_f32_dpp v144, v144, v144 row_bcast:15 row_mask:0xa bank_mask:0xf
	v_add_f32_dpp v145, v145, v145 row_bcast:15 row_mask:0xa bank_mask:0xf
	s_nop 0
	v_add_f32_dpp v144, v144, v144 row_bcast:31 row_mask:0xc bank_mask:0xf
	v_add_f32_dpp v145, v145, v145 row_bcast:31 row_mask:0xc bank_mask:0xf
	s_nop 0
	v_readlane_b32 s98, v144, 63
	v_readlane_b32 s99, v145, 63
	s_nop 1
	v_pk_add_f32 v[146:147], s[98:99], v[144:145] neg_lo:[0,1] neg_hi:[0,1]
	v_mul_f32_e64 v152, s98, v228
	v_mul_f32_e64 v153, s99, v228
	v_pk_mul_f32 v[146:147], v[146:147], v[228:229]
	v_exp_f32_e32 v152, v152
	v_exp_f32_e32 v153, v153
	v_exp_f32_e32 v146, v146
	v_exp_f32_e32 v147, v147
	s_nop 0
	v_pk_mul_f32 v[146:147], v[146:147], v[148:149]
	s_nop 0
	v_cvt_pk_bf16_f32 v150, v146, v147
	s_nop 0
	ds_write_b16 v172, v150 offset:0
	ds_write_b16_d16_hi v172, v150 offset:128
	s_and_saveexec_b64 s[20:21], vcc
	ds_write_b64 v163, v[152:153] offset:4096
	s_mov_b64 exec, s[20:21]
	s_waitcnt lgkmcnt(0)
	s_barrier
; #define MFMA16(a, b, c) __builtin_amdgcn_mfma_f32_16x16x32_bf16((a), (b), (c), 0, 0, 0)
;     ...
;         for (int n = 0; n < 64; ++n) {
;             const int buf = n & 1;
;             f32x4 a4[4]; bf16x8 vfr[2][2];
; #pragma unroll
;             for (int q = 0; q < 4; ++q) a4[q] = a4n[q];
;             const unsigned kraw = krawn;
; #pragma unroll
;             for (int e = 0; e < 2; ++e)
; #pragma unroll
;                 for (int ks = 0; ks < 2; ++ks) vfr[e][ks] = vfrn[e][ks];
;             if (n + 1 < 64) ldchunk(n + 1);
;             float cum[2];
; #pragma unroll
;             for (int e = 0; e < 2; ++e) {
;                 float z = bb[e];
; #pragma unroll
;                 for (int q = 0; q < 4; ++q) { z += a4[q].x * wa[e][4 * q] + a4[q].y * wa[e][4 * q + 1] + a4[q].z * wa[e][4 * q + 2] + a4[q].w * wa[e][4 * q + 3]; }
;                 cum[e] = (fminf(z, 0.f) - __logf(1.f + __expf(-fabsf(z)))) * (1.f / 16.f);
;             }
; #pragma unroll
;             for (int o = 1; o < 64; o <<= 1) {
;                 const float t0 = __shfl_up(cum[0], o), t1 = __shfl_up(cum[1], o);
;                 if (l >= o) { cum[0] += t0; cum[1] += t1; }
;             }
;             const float tot0 = __shfl(cum[0], 63), tot1 = __shfl(cum[1], 63);
;             kdl[(buf * 16 + 2 * w) * 64 + l] = f2bf(bf2f(kraw & 0xffffu) * __expf(tot0 - cum[0]));
;             kdl[(buf * 16 + 2 * w + 1) * 64 + l] = f2bf(bf2f(kraw >> 16) * __expf(tot1 - cum[1]));
;             if (l == 0) { decl[buf * 16 + 2 * w] = __expf(tot0); decl[buf * 16 + 2 * w + 1] = __expf(tot1); }
;             __syncthreads();
;             const f32x4 d4 = *(const f32x4*)(decl + buf * 16 + (l >> 4) * 4);
; #pragma unroll
;             for (int e = 0; e < 2; ++e) acc[e] = acc[e] * d4;
; #pragma unroll
;             for (int ks = 0; ks < 2; ++ks) {
;                 const bf16x8 af = *(const bf16x8*)(kdl + (buf * 16 + (l & 15)) * 64 + ks * 32 + (l >> 4) * 8);
; #pragma unroll
;                 for (int e = 0; e < 2; ++e) acc[e] = MFMA16(af, vfr[e][ks], acc[e]);
;             }
;             const int cidx = b * 64 + n;
; #pragma unroll
;             for (int e = 0; e < 2; ++e) {
;                 const int vv = (2 * w + e) * 16 + (l & 15);
;                 *(u32x2*)(ST + (((size_t)(cidx * 4 + hh)) * 256 + vv) * 128 + ksl * 16 + (l >> 4) * 4) = pk4(acc[e].x, acc[e].y, acc[e].z, acc[e].w);
;             }
	ds_read_b128 v[154:157], v75 offset:0
	ds_read_b128 v[240:243], v164 offset:4096
	ds_read_b128 v[236:239], v75 offset:64
	ds_read_b128 v[8:11], v29 offset:5120
	ds_read_b128 v[12:15], v29 offset:5136
	ds_read_b128 v[16:19], v29 offset:5152
	ds_read_b128 v[20:23], v29 offset:5168
	ds_read_b32 v24, v31 offset:2080
	s_waitcnt lgkmcnt(6)
	v_pk_mul_f32 v[0:1], v[0:1], v[240:241]
	v_pk_mul_f32 v[2:3], v[2:3], v[242:243]
	v_pk_mul_f32 v[4:5], v[4:5], v[240:241]
	v_pk_mul_f32 v[6:7], v[6:7], v[242:243]
	s_waitcnt vmcnt(8)
	s_nop 0
	v_mfma_f32_16x16x32_bf16 v[0:3], v[154:157], v[194:197], v[0:3]
	v_mfma_f32_16x16x32_bf16 v[4:7], v[154:157], v[202:205], v[4:7]
	s_waitcnt lgkmcnt(5)
	v_mfma_f32_16x16x32_bf16 v[0:3], v[236:239], v[198:201], v[0:3]
	v_mfma_f32_16x16x32_bf16 v[4:7], v[236:239], v[206:209], v[4:7]
	s_nop 7
	v_cvt_pk_bf16_f32 v244, v0, v1
	v_cvt_pk_bf16_f32 v245, v2, v3
	v_cvt_pk_bf16_f32 v246, v4, v5
	v_cvt_pk_bf16_f32 v247, v6, v7
	global_store_dwordx2 v234, v[244:245], s[100:101]
	global_store_dwordx2 v235, v[246:247], s[100:101]
	s_add_u32 s100, s100, 0x40000
	s_addc_u32 s101, s101, 0
	s_waitcnt lgkmcnt(0)
	v_pk_fma_f32 v[64:65], v[8:9], v[86:87], v[118:119] op_sel:[0,0,0] op_sel_hi:[0,1,1]
	v_pk_mul_f32 v[66:67], v[16:17], v[102:103] op_sel:[0,0] op_sel_hi:[0,1]
	v_pk_fma_f32 v[64:65], v[8:9], v[88:89], v[64:65] op_sel:[1,0,0] op_sel_hi:[1,1,1]
	v_pk_fma_f32 v[66:67], v[16:17], v[104:105], v[66:67] op_sel:[1,0,0] op_sel_hi:[1,1,1]
	v_pk_fma_f32 v[64:65], v[10:11], v[90:91], v[64:65] op_sel:[0,0,0] op_sel_hi:[0,1,1]
	v_pk_fma_f32 v[66:67], v[18:19], v[106:107], v[66:67] op_sel:[0,0,0] op_sel_hi:[0,1,1]
	v_pk_fma_f32 v[64:65], v[10:11], v[92:93], v[64:65] op_sel:[1,0,0] op_sel_hi:[1,1,1]
	v_pk_fma_f32 v[66:67], v[18:19], v[108:109], v[66:67] op_sel:[1,0,0] op_sel_hi:[1,1,1]
	v_pk_fma_f32 v[64:65], v[12:13], v[94:95], v[64:65] op_sel:[0,0,0] op_sel_hi:[0,1,1]
	v_pk_fma_f32 v[66:67], v[20:21], v[110:111], v[66:67] op_sel:[0,0,0] op_sel_hi:[0,1,1]
	v_pk_fma_f32 v[64:65], v[12:13], v[96:97], v[64:65] op_sel:[1,0,0] op_sel_hi:[1,1,1]
	v_pk_fma_f32 v[66:67], v[20:21], v[112:113], v[66:67] op_sel:[1,0,0] op_sel_hi:[1,1,1]
	v_pk_fma_f32 v[64:65], v[14:15], v[98:99], v[64:65] op_sel:[0,0,0] op_sel_hi:[0,1,1]
	v_pk_fma_f32 v[66:67], v[22:23], v[114:115], v[66:67] op_sel:[0,0,0] op_sel_hi:[0,1,1]
	v_pk_fma_f32 v[64:65], v[14:15], v[100:101], v[64:65] op_sel:[1,0,0] op_sel_hi:[1,1,1]
	v_pk_fma_f32 v[66:67], v[22:23], v[116:117], v[66:67] op_sel:[1,0,0] op_sel_hi:[1,1,1]
	v_lshlrev_b32_e32 v148, 16, v24
	v_pk_add_f32 v[64:65], v[64:65], v[66:67]
	v_and_b32_e32 v149, 0xffff0000, v24
	v_mul_f32_e64 v68, |v64|, v220
	v_mul_f32_e64 v69, |v65|, v220
	v_exp_f32_e32 v68, v68
	v_exp_f32_e32 v69, v69
	v_min_f32_e32 v70, 0, v64
	v_min_f32_e32 v71, 0, v65
	v_pk_add_f32 v[68:69], v[68:69], v[222:223]
	s_nop 0
	v_log_f32_e32 v138, v68
	v_log_f32_e32 v139, v69
	s_nop 0
	v_pk_mul_f32 v[140:141], v[138:139], v[224:225]
	s_nop 0
	v_pk_fma_f32 v[142:143], v[138:139], v[224:225], v[140:141] neg_lo:[0,0,1] neg_hi:[0,0,1]
	s_nop 0
	v_pk_fma_f32 v[142:143], v[138:139], v[226:227], v[142:143]
	s_nop 0
	v_pk_fma_f32 v[142:143], v[138:139], v[224:225], v[142:143]
	s_nop 0
	v_pk_add_f32 v[144:145], v[70:71], v[142:143] neg_lo:[0,1] neg_hi:[0,1]
	s_nop 0
	v_pk_mul_f32 v[144:145], v[144:145], v[214:215]
	s_nop 1
	v_add_f32_dpp v144, v144, v144 row_shr:1 row_mask:0xf bank_mask:0xf
	v_add_f32_dpp v145, v145, v145 row_shr:1 row_mask:0xf bank_mask:0xf
	s_nop 0
	v_add_f32_dpp v144, v144, v144 row_shr:2 row_mask:0xf bank_mask:0xf
	v_add_f32_dpp v145, v145, v145 row_shr:2 row_mask:0xf bank_mask:0xf
	s_nop 0
	v_add_f32_dpp v144, v144, v144 row_shr:4 row_mask:0xf bank_mask:0xf
	v_add_f32_dpp v145, v145, v145 row_shr:4 row_mask:0xf bank_mask:0xf
	s_nop 0
	v_add_f32_dpp v144, v144, v144 row_shr:8 row_mask:0xf bank_mask:0xf
	v_add_f32_dpp v145, v145, v145 row_shr:8 row_mask:0xf bank_mask:0xf
	s_nop 0
	v_add_f32_dpp v144, v144, v144 row_bcast:15 row_mask:0xa bank_mask:0xf
	v_add_f32_dpp v145, v145, v145 row_bcast:15 row_mask:0xa bank_mask:0xf
	s_nop 0
	v_add_f32_dpp v144, v144, v144 row_bcast:31 row_mask:0xc bank_mask:0xf
	v_add_f32_dpp v145, v145, v145 row_bcast:31 row_mask:0xc bank_mask:0xf
	s_nop 0
	v_readlane_b32 s98, v144, 63
	v_readlane_b32 s99, v145, 63
	s_nop 1
	v_pk_add_f32 v[146:147], s[98:99], v[144:145] neg_lo:[0,1] neg_hi:[0,1]
	v_mul_f32_e64 v152, s98, v228
	v_mul_f32_e64 v153, s99, v228
	v_pk_mul_f32 v[146:147], v[146:147], v[228:229]
	v_exp_f32_e32 v152, v152
	v_exp_f32_e32 v153, v153
	v_exp_f32_e32 v146, v146
	v_exp_f32_e32 v147, v147
	s_nop 0
	v_pk_mul_f32 v[146:147], v[146:147], v[148:149]
	s_nop 0
	v_cvt_pk_bf16_f32 v150, v146, v147
	s_nop 0
	ds_write_b16 v172, v150 offset:2048
	ds_write_b16_d16_hi v172, v150 offset:2176
	s_and_saveexec_b64 s[20:21], vcc
	ds_write_b64 v163, v[152:153] offset:4160
	s_mov_b64 exec, s[20:21]
	s_waitcnt lgkmcnt(0)
	s_barrier
	ds_read_b128 v[154:157], v75 offset:2048
	ds_read_b128 v[240:243], v164 offset:4160
	ds_read_b128 v[236:239], v75 offset:2112
	s_waitcnt lgkmcnt(1)
	v_pk_mul_f32 v[0:1], v[0:1], v[240:241]
	v_pk_mul_f32 v[2:3], v[2:3], v[242:243]
	v_pk_mul_f32 v[4:5], v[4:5], v[240:241]
	v_pk_mul_f32 v[6:7], v[6:7], v[242:243]
	s_waitcnt vmcnt(4)
	s_nop 0
	v_mfma_f32_16x16x32_bf16 v[0:3], v[154:157], v[32:35], v[0:3]
	v_mfma_f32_16x16x32_bf16 v[4:7], v[154:157], v[40:43], v[4:7]
	s_waitcnt lgkmcnt(0)
	v_mfma_f32_16x16x32_bf16 v[0:3], v[236:239], v[36:39], v[0:3]
	v_mfma_f32_16x16x32_bf16 v[4:7], v[236:239], v[44:47], v[4:7]
	s_nop 7
	v_cvt_pk_bf16_f32 v244, v0, v1
	v_cvt_pk_bf16_f32 v245, v2, v3
	v_cvt_pk_bf16_f32 v246, v4, v5
	v_cvt_pk_bf16_f32 v247, v6, v7
	global_store_dwordx2 v234, v[244:245], s[100:101]
	global_store_dwordx2 v235, v[246:247], s[100:101]
	s_add_u32 s100, s100, 0x40000
	s_addc_u32 s101, s101, 0
	s_add_i32 s56, s56, s96
	s_cmpk_gt_i32 s56, 0xff
	s_cbranch_scc0 .LBB0_418
